# instruction-fetch warming moved into each GEMM K-loop's last iteration (one iteration of lead) plus the first K-loop's entry
# speedup vs baseline: 1.0435x; 1.0012x over previous
.LBB0_353:
	s_waitcnt lgkmcnt(0)
	ds_read_b128 v[130:133], v189
	ds_read_b128 v[168:171], v189 offset:1024
	ds_read_b128 v[172:175], v189 offset:2048
	ds_read_b128 v[176:179], v189 offset:3072
	ds_read_b128 v[180:183], v190
	ds_read_b128 v[184:187], v190 offset:1024
	ds_read_b128 v[194:197], v190 offset:2048
	ds_read_b128 v[200:203], v190 offset:3072
	s_add_i32 s40, s10, 2
	s_add_u32 s41, s8, 0x80
	s_addc_u32 s11, s9, 0
	s_cmp_eq_u32 s87, s10
	s_cselect_b32 s10, s3, s41
	s_cselect_b32 s11, s1, s11
	s_cselect_b32 s61, s12, s15
	s_cselect_b32 s60, s13, s14
	s_cbranch_scc0 .Lpf_skip_0
	s_getpc_b64 s[98:99]
	s_mov_b32 m0, 0x22800
	v_lshlrev_b32_e32 v236, 7, v0
	global_load_lds_dword v236, s[98:99]
.Lpf_skip_0:
	v_lshl_add_u64 v[236:237], s[8:9], 0, v[164:165]
	s_add_i32 m0, s23, 0xc000
	ds_read_b128 v[204:207], v188
	ds_read_b128 v[208:211], v188 offset:1024
	ds_read_b128 v[212:215], v188 offset:2048
	ds_read_b128 v[216:219], v188 offset:3072
	ds_read_b128 v[220:223], v188 offset:4096
	ds_read_b128 v[224:227], v188 offset:5120
	ds_read_b128 v[228:231], v188 offset:6144
	ds_read_b128 v[232:235], v188 offset:7168
	global_load_lds_dwordx4 v[236:237], off
	v_lshl_add_u64 v[236:237], s[8:9], 0, v[166:167]
	s_add_i32 m0, s23, 0xe000
	s_nop 0
	global_load_lds_dwordx4 v[236:237], off
	s_waitcnt vmcnt(8)
	s_waitcnt lgkmcnt(0)
	s_barrier
	s_setprio 1
	s_waitcnt lgkmcnt(0)
	v_mfma_f32_16x16x32_bf16 v[122:125], v[130:133], v[204:207], v[122:125]
	v_mfma_f32_16x16x32_bf16 v[126:129], v[172:175], v[204:207], v[126:129]
	v_mfma_f32_16x16x32_bf16 v[118:121], v[130:133], v[212:215], v[118:121]
	v_mfma_f32_16x16x32_bf16 v[114:117], v[172:175], v[212:215], v[114:117]
	v_mfma_f32_16x16x32_bf16 v[110:113], v[130:133], v[220:223], v[110:113]
	v_mfma_f32_16x16x32_bf16 v[106:109], v[172:175], v[220:223], v[106:109]
	v_mfma_f32_16x16x32_bf16 v[102:105], v[130:133], v[228:231], v[102:105]
	v_mfma_f32_16x16x32_bf16 v[98:101], v[172:175], v[228:231], v[98:101]
	v_mfma_f32_16x16x32_bf16 v[122:125], v[168:171], v[208:211], v[122:125]
	v_mfma_f32_16x16x32_bf16 v[126:129], v[176:179], v[208:211], v[126:129]
	v_mfma_f32_16x16x32_bf16 v[118:121], v[168:171], v[216:219], v[118:121]
	v_mfma_f32_16x16x32_bf16 v[114:117], v[176:179], v[216:219], v[114:117]
	v_mfma_f32_16x16x32_bf16 v[110:113], v[168:171], v[224:227], v[110:113]
	v_mfma_f32_16x16x32_bf16 v[106:109], v[176:179], v[224:227], v[106:109]
	v_mfma_f32_16x16x32_bf16 v[102:105], v[168:171], v[232:235], v[102:105]
	v_mfma_f32_16x16x32_bf16 v[98:101], v[176:179], v[232:235], v[98:101]
	s_setprio 0
	s_setprio 1
	v_mfma_f32_16x16x32_bf16 v[62:65], v[180:183], v[204:207], v[62:65]
	v_mfma_f32_16x16x32_bf16 v[58:61], v[194:197], v[204:207], v[58:61]
	v_mfma_f32_16x16x32_bf16 v[54:57], v[180:183], v[212:215], v[54:57]
	v_mfma_f32_16x16x32_bf16 v[50:53], v[194:197], v[212:215], v[50:53]
	v_mfma_f32_16x16x32_bf16 v[46:49], v[180:183], v[220:223], v[46:49]
	v_mfma_f32_16x16x32_bf16 v[42:45], v[194:197], v[220:223], v[42:45]
	v_mfma_f32_16x16x32_bf16 v[38:41], v[180:183], v[228:231], v[38:41]
	v_mfma_f32_16x16x32_bf16 v[34:37], v[194:197], v[228:231], v[34:37]
	v_mfma_f32_16x16x32_bf16 v[62:65], v[184:187], v[208:211], v[62:65]
	v_mfma_f32_16x16x32_bf16 v[58:61], v[200:203], v[208:211], v[58:61]
	v_mfma_f32_16x16x32_bf16 v[54:57], v[184:187], v[216:219], v[54:57]
	v_mfma_f32_16x16x32_bf16 v[50:53], v[200:203], v[216:219], v[50:53]
	v_mfma_f32_16x16x32_bf16 v[46:49], v[184:187], v[224:227], v[46:49]
	v_mfma_f32_16x16x32_bf16 v[42:45], v[200:203], v[224:227], v[42:45]
	v_mfma_f32_16x16x32_bf16 v[38:41], v[184:187], v[232:235], v[38:41]
	v_mfma_f32_16x16x32_bf16 v[34:37], v[200:203], v[232:235], v[34:37]
	s_setprio 0
	s_barrier
	s_add_i32 s41, s86, s90
	v_lshl_add_u64 v[236:237], s[60:61], 0, v[136:137]
	s_mov_b32 m0, s41
	ds_read_b128 v[204:207], v188 offset:16384
	ds_read_b128 v[208:211], v188 offset:17408
	ds_read_b128 v[212:215], v188 offset:18432
	ds_read_b128 v[216:219], v188 offset:19456
	ds_read_b128 v[220:223], v188 offset:20480
	ds_read_b128 v[224:227], v188 offset:21504
	ds_read_b128 v[228:231], v188 offset:22528
	ds_read_b128 v[232:235], v188 offset:23552
	global_load_lds_dwordx4 v[236:237], off
	s_add_i32 m0, s41, 0x2000
	v_lshl_add_u64 v[238:239], s[60:61], 0, v[140:141]
	s_add_u32 s60, s60, s20
	s_addc_u32 s61, s61, s21
	s_add_i32 s41, s33, s90
	global_load_lds_dwordx4 v[238:239], off
	v_lshl_add_u64 v[240:241], s[60:61], 0, v[136:137]
	s_mov_b32 m0, s41
	v_lshl_add_u64 v[242:243], s[60:61], 0, v[140:141]
	global_load_lds_dwordx4 v[240:241], off
	s_add_i32 m0, s41, 0x2000
	v_lshl_add_u64 v[244:245], s[10:11], 0, v[134:135]
	global_load_lds_dwordx4 v[242:243], off
	s_mov_b32 m0, s23
	v_lshl_add_u64 v[246:247], s[10:11], 0, v[138:139]
	global_load_lds_dwordx4 v[244:245], off
	s_mov_b32 m0, s31
	s_nop 0
	global_load_lds_dwordx4 v[246:247], off
	s_waitcnt vmcnt(8)
	s_waitcnt lgkmcnt(0)
	s_barrier
	s_setprio 1
	s_waitcnt lgkmcnt(0)
	v_mfma_f32_16x16x32_bf16 v[94:97], v[130:133], v[204:207], v[94:97]
	v_mfma_f32_16x16x32_bf16 v[90:93], v[172:175], v[204:207], v[90:93]
	v_mfma_f32_16x16x32_bf16 v[86:89], v[130:133], v[212:215], v[86:89]
	v_mfma_f32_16x16x32_bf16 v[82:85], v[172:175], v[212:215], v[82:85]
	v_mfma_f32_16x16x32_bf16 v[78:81], v[130:133], v[220:223], v[78:81]
	v_mfma_f32_16x16x32_bf16 v[74:77], v[172:175], v[220:223], v[74:77]
	v_mfma_f32_16x16x32_bf16 v[70:73], v[130:133], v[228:231], v[70:73]
	v_mfma_f32_16x16x32_bf16 v[66:69], v[172:175], v[228:231], v[66:69]
	v_mfma_f32_16x16x32_bf16 v[94:97], v[168:171], v[208:211], v[94:97]
	v_mfma_f32_16x16x32_bf16 v[90:93], v[176:179], v[208:211], v[90:93]
	v_mfma_f32_16x16x32_bf16 v[86:89], v[168:171], v[216:219], v[86:89]
	v_mfma_f32_16x16x32_bf16 v[82:85], v[176:179], v[216:219], v[82:85]
	v_mfma_f32_16x16x32_bf16 v[78:81], v[168:171], v[224:227], v[78:81]
	v_mfma_f32_16x16x32_bf16 v[74:77], v[176:179], v[224:227], v[74:77]
	v_mfma_f32_16x16x32_bf16 v[70:73], v[168:171], v[232:235], v[70:73]
	v_mfma_f32_16x16x32_bf16 v[66:69], v[176:179], v[232:235], v[66:69]
	s_setprio 0
	s_setprio 1
	v_mfma_f32_16x16x32_bf16 v[30:33], v[180:183], v[204:207], v[30:33]
	v_mfma_f32_16x16x32_bf16 v[26:29], v[194:197], v[204:207], v[26:29]
	v_mfma_f32_16x16x32_bf16 v[22:25], v[180:183], v[212:215], v[22:25]
	v_mfma_f32_16x16x32_bf16 v[18:21], v[194:197], v[212:215], v[18:21]
	v_mfma_f32_16x16x32_bf16 v[14:17], v[180:183], v[220:223], v[14:17]
	v_mfma_f32_16x16x32_bf16 v[10:13], v[194:197], v[220:223], v[10:13]
	v_mfma_f32_16x16x32_bf16 v[6:9], v[180:183], v[228:231], v[6:9]
	v_mfma_f32_16x16x32_bf16 v[2:5], v[194:197], v[228:231], v[2:5]
	v_mfma_f32_16x16x32_bf16 v[30:33], v[184:187], v[208:211], v[30:33]
	v_mfma_f32_16x16x32_bf16 v[26:29], v[200:203], v[208:211], v[26:29]
	v_mfma_f32_16x16x32_bf16 v[22:25], v[184:187], v[216:219], v[22:25]
	v_mfma_f32_16x16x32_bf16 v[18:21], v[200:203], v[216:219], v[18:21]
	v_mfma_f32_16x16x32_bf16 v[14:17], v[184:187], v[224:227], v[14:17]
	v_mfma_f32_16x16x32_bf16 v[10:13], v[200:203], v[224:227], v[10:13]
	v_mfma_f32_16x16x32_bf16 v[6:9], v[184:187], v[232:235], v[6:9]
	v_mfma_f32_16x16x32_bf16 v[2:5], v[200:203], v[232:235], v[2:5]
	s_setprio 0
	s_barrier
	s_add_i32 s41, 0, 0x18000
	v_add_u32_e32 v142, s41, v145
	s_add_i32 s51, 0, 0x1c000
	ds_read_b128 v[130:133], v142
	ds_read_b128 v[168:171], v142 offset:1024
	ds_read_b128 v[172:175], v142 offset:2048
	ds_read_b128 v[176:179], v142 offset:3072
	v_add_u32_e32 v142, s51, v145
	ds_read_b128 v[180:183], v142
	ds_read_b128 v[184:187], v142 offset:1024
	ds_read_b128 v[194:197], v142 offset:2048
	ds_read_b128 v[200:203], v142 offset:3072
	s_add_u32 s10, s10, s20
	s_addc_u32 s11, s11, s21
	s_mov_b32 m0, s91
	v_lshl_add_u64 v[248:249], s[10:11], 0, v[134:135]
	ds_read_b128 v[204:207], v188 offset:32768
	ds_read_b128 v[208:211], v188 offset:33792
	ds_read_b128 v[212:215], v188 offset:34816
	ds_read_b128 v[216:219], v188 offset:35840
	ds_read_b128 v[220:223], v188 offset:36864
	ds_read_b128 v[224:227], v188 offset:37888
	ds_read_b128 v[228:231], v188 offset:38912
	ds_read_b128 v[232:235], v188 offset:39936
	global_load_lds_dwordx4 v[248:249], off
	v_lshl_add_u64 v[248:249], s[10:11], 0, v[138:139]
	s_mov_b32 m0, s92
	s_nop 0
	global_load_lds_dwordx4 v[248:249], off
	s_waitcnt vmcnt(8)
	s_waitcnt lgkmcnt(0)
	s_barrier
	s_setprio 1
	s_waitcnt lgkmcnt(0)
	v_mfma_f32_16x16x32_bf16 v[122:125], v[130:133], v[204:207], v[122:125]
	v_mfma_f32_16x16x32_bf16 v[126:129], v[172:175], v[204:207], v[126:129]
	v_mfma_f32_16x16x32_bf16 v[118:121], v[130:133], v[212:215], v[118:121]
	v_mfma_f32_16x16x32_bf16 v[114:117], v[172:175], v[212:215], v[114:117]
	v_mfma_f32_16x16x32_bf16 v[110:113], v[130:133], v[220:223], v[110:113]
	v_mfma_f32_16x16x32_bf16 v[106:109], v[172:175], v[220:223], v[106:109]
	v_mfma_f32_16x16x32_bf16 v[102:105], v[130:133], v[228:231], v[102:105]
	v_mfma_f32_16x16x32_bf16 v[98:101], v[172:175], v[228:231], v[98:101]
	v_mfma_f32_16x16x32_bf16 v[122:125], v[168:171], v[208:211], v[122:125]
	v_mfma_f32_16x16x32_bf16 v[126:129], v[176:179], v[208:211], v[126:129]
	v_mfma_f32_16x16x32_bf16 v[118:121], v[168:171], v[216:219], v[118:121]
	v_mfma_f32_16x16x32_bf16 v[114:117], v[176:179], v[216:219], v[114:117]
	v_mfma_f32_16x16x32_bf16 v[110:113], v[168:171], v[224:227], v[110:113]
	v_mfma_f32_16x16x32_bf16 v[106:109], v[176:179], v[224:227], v[106:109]
	v_mfma_f32_16x16x32_bf16 v[102:105], v[168:171], v[232:235], v[102:105]
	v_mfma_f32_16x16x32_bf16 v[98:101], v[176:179], v[232:235], v[98:101]
	s_setprio 0
	s_setprio 1
	v_mfma_f32_16x16x32_bf16 v[62:65], v[180:183], v[204:207], v[62:65]
	v_mfma_f32_16x16x32_bf16 v[58:61], v[194:197], v[204:207], v[58:61]
	v_mfma_f32_16x16x32_bf16 v[54:57], v[180:183], v[212:215], v[54:57]
	v_mfma_f32_16x16x32_bf16 v[50:53], v[194:197], v[212:215], v[50:53]
	v_mfma_f32_16x16x32_bf16 v[46:49], v[180:183], v[220:223], v[46:49]
	v_mfma_f32_16x16x32_bf16 v[42:45], v[194:197], v[220:223], v[42:45]
	v_mfma_f32_16x16x32_bf16 v[38:41], v[180:183], v[228:231], v[38:41]
	v_mfma_f32_16x16x32_bf16 v[34:37], v[194:197], v[228:231], v[34:37]
	v_mfma_f32_16x16x32_bf16 v[62:65], v[184:187], v[208:211], v[62:65]
	v_mfma_f32_16x16x32_bf16 v[58:61], v[200:203], v[208:211], v[58:61]
	v_mfma_f32_16x16x32_bf16 v[54:57], v[184:187], v[216:219], v[54:57]
	v_mfma_f32_16x16x32_bf16 v[50:53], v[200:203], v[216:219], v[50:53]
	v_mfma_f32_16x16x32_bf16 v[46:49], v[184:187], v[224:227], v[46:49]
	v_mfma_f32_16x16x32_bf16 v[42:45], v[200:203], v[224:227], v[42:45]
	v_mfma_f32_16x16x32_bf16 v[38:41], v[184:187], v[232:235], v[38:41]
	v_mfma_f32_16x16x32_bf16 v[34:37], v[200:203], v[232:235], v[34:37]
	s_setprio 0
	s_barrier
	s_add_i32 s10, s41, s90
	v_lshl_add_u64 v[236:237], v[236:237], 0, s[26:27]
	s_mov_b32 m0, s10
	ds_read_b128 v[204:207], v188 offset:49152
	ds_read_b128 v[208:211], v188 offset:50176
	ds_read_b128 v[212:215], v188 offset:51200
	ds_read_b128 v[216:219], v188 offset:52224
	ds_read_b128 v[220:223], v188 offset:53248
	ds_read_b128 v[224:227], v188 offset:54272
	ds_read_b128 v[228:231], v188 offset:55296
	ds_read_b128 v[232:235], v188 offset:56320
	global_load_lds_dwordx4 v[236:237], off
	v_lshl_add_u64 v[236:237], v[238:239], 0, s[26:27]
	s_add_i32 m0, s10, 0x2000
	s_add_i32 s10, s51, s90
	global_load_lds_dwordx4 v[236:237], off
	v_lshl_add_u64 v[236:237], v[240:241], 0, s[26:27]
	s_mov_b32 m0, s10
	s_nop 0
	global_load_lds_dwordx4 v[236:237], off
	v_lshl_add_u64 v[236:237], v[242:243], 0, s[26:27]
	s_add_i32 m0, s10, 0x2000
	s_nop 0
	global_load_lds_dwordx4 v[236:237], off
	v_lshl_add_u64 v[236:237], v[244:245], 0, s[26:27]
	s_mov_b32 m0, s97
	s_nop 0
	global_load_lds_dwordx4 v[236:237], off
	v_lshl_add_u64 v[236:237], v[246:247], 0, s[26:27]
	s_mov_b32 m0, s89
	s_nop 0
	global_load_lds_dwordx4 v[236:237], off
	s_waitcnt vmcnt(8)
	s_waitcnt lgkmcnt(0)
	s_barrier
	s_setprio 1
	s_waitcnt lgkmcnt(0)
	v_mfma_f32_16x16x32_bf16 v[94:97], v[130:133], v[204:207], v[94:97]
	v_mfma_f32_16x16x32_bf16 v[90:93], v[172:175], v[204:207], v[90:93]
	v_mfma_f32_16x16x32_bf16 v[86:89], v[130:133], v[212:215], v[86:89]
	v_mfma_f32_16x16x32_bf16 v[82:85], v[172:175], v[212:215], v[82:85]
	v_mfma_f32_16x16x32_bf16 v[78:81], v[130:133], v[220:223], v[78:81]
	v_mfma_f32_16x16x32_bf16 v[74:77], v[172:175], v[220:223], v[74:77]
	v_mfma_f32_16x16x32_bf16 v[70:73], v[130:133], v[228:231], v[70:73]
	v_mfma_f32_16x16x32_bf16 v[66:69], v[172:175], v[228:231], v[66:69]
	v_mfma_f32_16x16x32_bf16 v[94:97], v[168:171], v[208:211], v[94:97]
	v_mfma_f32_16x16x32_bf16 v[90:93], v[176:179], v[208:211], v[90:93]
	v_mfma_f32_16x16x32_bf16 v[86:89], v[168:171], v[216:219], v[86:89]
	v_mfma_f32_16x16x32_bf16 v[82:85], v[176:179], v[216:219], v[82:85]
	v_mfma_f32_16x16x32_bf16 v[78:81], v[168:171], v[224:227], v[78:81]
	v_mfma_f32_16x16x32_bf16 v[74:77], v[176:179], v[224:227], v[74:77]
	v_mfma_f32_16x16x32_bf16 v[70:73], v[168:171], v[232:235], v[70:73]
	v_mfma_f32_16x16x32_bf16 v[66:69], v[176:179], v[232:235], v[66:69]
	s_setprio 0
	s_setprio 1
	v_mfma_f32_16x16x32_bf16 v[30:33], v[180:183], v[204:207], v[30:33]
	v_mfma_f32_16x16x32_bf16 v[26:29], v[194:197], v[204:207], v[26:29]
	v_mfma_f32_16x16x32_bf16 v[22:25], v[180:183], v[212:215], v[22:25]
	v_mfma_f32_16x16x32_bf16 v[18:21], v[194:197], v[212:215], v[18:21]
	v_mfma_f32_16x16x32_bf16 v[14:17], v[180:183], v[220:223], v[14:17]
	v_mfma_f32_16x16x32_bf16 v[10:13], v[194:197], v[220:223], v[10:13]
	v_mfma_f32_16x16x32_bf16 v[6:9], v[180:183], v[228:231], v[6:9]
	v_mfma_f32_16x16x32_bf16 v[2:5], v[194:197], v[228:231], v[2:5]
	v_mfma_f32_16x16x32_bf16 v[30:33], v[184:187], v[208:211], v[30:33]
	v_mfma_f32_16x16x32_bf16 v[26:29], v[200:203], v[208:211], v[26:29]
	v_mfma_f32_16x16x32_bf16 v[22:25], v[184:187], v[216:219], v[22:25]
	v_mfma_f32_16x16x32_bf16 v[18:21], v[200:203], v[216:219], v[18:21]
	v_mfma_f32_16x16x32_bf16 v[14:17], v[184:187], v[224:227], v[14:17]
	v_mfma_f32_16x16x32_bf16 v[10:13], v[200:203], v[224:227], v[10:13]
	v_mfma_f32_16x16x32_bf16 v[6:9], v[184:187], v[232:235], v[6:9]
	v_mfma_f32_16x16x32_bf16 v[2:5], v[200:203], v[232:235], v[2:5]
	s_setprio 0
	s_barrier
	s_add_u32 s8, s8, 0x100
	s_addc_u32 s9, s9, 0
	s_add_u32 s14, s14, 0x100
	s_addc_u32 s15, s15, 0
	s_cmp_ge_i32 s40, s74
	s_mov_b32 s10, s40
	s_cbranch_scc0 .LBB0_353

.LBB0_867:
	s_waitcnt lgkmcnt(0)
	ds_read_b128 v[130:133], v189
	ds_read_b128 v[168:171], v189 offset:1024
	ds_read_b128 v[172:175], v189 offset:2048
	ds_read_b128 v[176:179], v189 offset:3072
	ds_read_b128 v[180:183], v190
	ds_read_b128 v[184:187], v190 offset:1024
	ds_read_b128 v[194:197], v190 offset:2048
	ds_read_b128 v[200:203], v190 offset:3072
	s_add_i32 s45, s10, 2
	s_add_u32 s55, s8, 0x80
	s_addc_u32 s11, s9, 0
	s_cmp_eq_u32 s87, s10
	s_cselect_b32 s10, s12, s55
	s_cselect_b32 s11, s3, s11
	s_cselect_b32 s65, s13, s44
	s_cselect_b32 s64, s14, s15
	s_cbranch_scc0 .Lpf_skip_1
	s_getpc_b64 s[98:99]
	s_mov_b32 m0, 0x22800
	v_lshlrev_b32_e32 v236, 7, v0
	global_load_lds_dword v236, s[98:99]
.Lpf_skip_1:
	v_lshl_add_u64 v[236:237], s[8:9], 0, v[164:165]
	s_add_i32 m0, s27, 0xc000
	ds_read_b128 v[204:207], v188
	ds_read_b128 v[208:211], v188 offset:1024
	ds_read_b128 v[212:215], v188 offset:2048
	ds_read_b128 v[216:219], v188 offset:3072
	ds_read_b128 v[220:223], v188 offset:4096
	ds_read_b128 v[224:227], v188 offset:5120
	ds_read_b128 v[228:231], v188 offset:6144
	ds_read_b128 v[232:235], v188 offset:7168
	global_load_lds_dwordx4 v[236:237], off
	v_lshl_add_u64 v[236:237], s[8:9], 0, v[166:167]
	s_add_i32 m0, s27, 0xe000
	s_nop 0
	global_load_lds_dwordx4 v[236:237], off
	s_waitcnt vmcnt(8)
	s_waitcnt lgkmcnt(0)
	s_barrier
	s_setprio 1
	s_waitcnt lgkmcnt(0)
	v_mfma_f32_16x16x32_bf16 v[122:125], v[130:133], v[204:207], v[122:125]
	v_mfma_f32_16x16x32_bf16 v[126:129], v[172:175], v[204:207], v[126:129]
	v_mfma_f32_16x16x32_bf16 v[118:121], v[130:133], v[212:215], v[118:121]
	v_mfma_f32_16x16x32_bf16 v[114:117], v[172:175], v[212:215], v[114:117]
	v_mfma_f32_16x16x32_bf16 v[110:113], v[130:133], v[220:223], v[110:113]
	v_mfma_f32_16x16x32_bf16 v[106:109], v[172:175], v[220:223], v[106:109]
	v_mfma_f32_16x16x32_bf16 v[102:105], v[130:133], v[228:231], v[102:105]
	v_mfma_f32_16x16x32_bf16 v[98:101], v[172:175], v[228:231], v[98:101]
	v_mfma_f32_16x16x32_bf16 v[122:125], v[168:171], v[208:211], v[122:125]
	v_mfma_f32_16x16x32_bf16 v[126:129], v[176:179], v[208:211], v[126:129]
	v_mfma_f32_16x16x32_bf16 v[118:121], v[168:171], v[216:219], v[118:121]
	v_mfma_f32_16x16x32_bf16 v[114:117], v[176:179], v[216:219], v[114:117]
	v_mfma_f32_16x16x32_bf16 v[110:113], v[168:171], v[224:227], v[110:113]
	v_mfma_f32_16x16x32_bf16 v[106:109], v[176:179], v[224:227], v[106:109]
	v_mfma_f32_16x16x32_bf16 v[102:105], v[168:171], v[232:235], v[102:105]
	v_mfma_f32_16x16x32_bf16 v[98:101], v[176:179], v[232:235], v[98:101]
	s_setprio 0
	s_setprio 1
	v_mfma_f32_16x16x32_bf16 v[62:65], v[180:183], v[204:207], v[62:65]
	v_mfma_f32_16x16x32_bf16 v[58:61], v[194:197], v[204:207], v[58:61]
	v_mfma_f32_16x16x32_bf16 v[54:57], v[180:183], v[212:215], v[54:57]
	v_mfma_f32_16x16x32_bf16 v[50:53], v[194:197], v[212:215], v[50:53]
	v_mfma_f32_16x16x32_bf16 v[46:49], v[180:183], v[220:223], v[46:49]
	v_mfma_f32_16x16x32_bf16 v[42:45], v[194:197], v[220:223], v[42:45]
	v_mfma_f32_16x16x32_bf16 v[38:41], v[180:183], v[228:231], v[38:41]
	v_mfma_f32_16x16x32_bf16 v[34:37], v[194:197], v[228:231], v[34:37]
	v_mfma_f32_16x16x32_bf16 v[62:65], v[184:187], v[208:211], v[62:65]
	v_mfma_f32_16x16x32_bf16 v[58:61], v[200:203], v[208:211], v[58:61]
	v_mfma_f32_16x16x32_bf16 v[54:57], v[184:187], v[216:219], v[54:57]
	v_mfma_f32_16x16x32_bf16 v[50:53], v[200:203], v[216:219], v[50:53]
	v_mfma_f32_16x16x32_bf16 v[46:49], v[184:187], v[224:227], v[46:49]
	v_mfma_f32_16x16x32_bf16 v[42:45], v[200:203], v[224:227], v[42:45]
	v_mfma_f32_16x16x32_bf16 v[38:41], v[184:187], v[232:235], v[38:41]
	v_mfma_f32_16x16x32_bf16 v[34:37], v[200:203], v[232:235], v[34:37]
	s_setprio 0
	s_barrier
	s_add_i32 s55, s16, s93
	v_lshl_add_u64 v[236:237], s[64:65], 0, v[136:137]
	s_mov_b32 m0, s55
	ds_read_b128 v[204:207], v188 offset:16384
	ds_read_b128 v[208:211], v188 offset:17408
	ds_read_b128 v[212:215], v188 offset:18432
	ds_read_b128 v[216:219], v188 offset:19456
	ds_read_b128 v[220:223], v188 offset:20480
	ds_read_b128 v[224:227], v188 offset:21504
	ds_read_b128 v[228:231], v188 offset:22528
	ds_read_b128 v[232:235], v188 offset:23552
	global_load_lds_dwordx4 v[236:237], off
	s_add_i32 m0, s55, 0x2000
	v_lshl_add_u64 v[238:239], s[64:65], 0, v[140:141]
	s_add_u32 s64, s64, s24
	s_addc_u32 s65, s65, s25
	s_add_i32 s55, s19, s93
	global_load_lds_dwordx4 v[238:239], off
	v_lshl_add_u64 v[240:241], s[64:65], 0, v[136:137]
	s_mov_b32 m0, s55
	v_lshl_add_u64 v[242:243], s[64:65], 0, v[140:141]
	global_load_lds_dwordx4 v[240:241], off
	s_add_i32 m0, s55, 0x2000
	v_lshl_add_u64 v[244:245], s[10:11], 0, v[134:135]
	global_load_lds_dwordx4 v[242:243], off
	s_mov_b32 m0, s27
	v_lshl_add_u64 v[246:247], s[10:11], 0, v[138:139]
	global_load_lds_dwordx4 v[244:245], off
	s_mov_b32 m0, s35
	s_nop 0
	global_load_lds_dwordx4 v[246:247], off
	s_waitcnt vmcnt(8)
	s_waitcnt lgkmcnt(0)
	s_barrier
	s_setprio 1
	s_waitcnt lgkmcnt(0)
	v_mfma_f32_16x16x32_bf16 v[94:97], v[130:133], v[204:207], v[94:97]
	v_mfma_f32_16x16x32_bf16 v[90:93], v[172:175], v[204:207], v[90:93]
	v_mfma_f32_16x16x32_bf16 v[86:89], v[130:133], v[212:215], v[86:89]
	v_mfma_f32_16x16x32_bf16 v[82:85], v[172:175], v[212:215], v[82:85]
	v_mfma_f32_16x16x32_bf16 v[78:81], v[130:133], v[220:223], v[78:81]
	v_mfma_f32_16x16x32_bf16 v[74:77], v[172:175], v[220:223], v[74:77]
	v_mfma_f32_16x16x32_bf16 v[70:73], v[130:133], v[228:231], v[70:73]
	v_mfma_f32_16x16x32_bf16 v[66:69], v[172:175], v[228:231], v[66:69]
	v_mfma_f32_16x16x32_bf16 v[94:97], v[168:171], v[208:211], v[94:97]
	v_mfma_f32_16x16x32_bf16 v[90:93], v[176:179], v[208:211], v[90:93]
	v_mfma_f32_16x16x32_bf16 v[86:89], v[168:171], v[216:219], v[86:89]
	v_mfma_f32_16x16x32_bf16 v[82:85], v[176:179], v[216:219], v[82:85]
	v_mfma_f32_16x16x32_bf16 v[78:81], v[168:171], v[224:227], v[78:81]
	v_mfma_f32_16x16x32_bf16 v[74:77], v[176:179], v[224:227], v[74:77]
	v_mfma_f32_16x16x32_bf16 v[70:73], v[168:171], v[232:235], v[70:73]
	v_mfma_f32_16x16x32_bf16 v[66:69], v[176:179], v[232:235], v[66:69]
	s_setprio 0
	s_setprio 1
	v_mfma_f32_16x16x32_bf16 v[30:33], v[180:183], v[204:207], v[30:33]
	v_mfma_f32_16x16x32_bf16 v[26:29], v[194:197], v[204:207], v[26:29]
	v_mfma_f32_16x16x32_bf16 v[22:25], v[180:183], v[212:215], v[22:25]
	v_mfma_f32_16x16x32_bf16 v[18:21], v[194:197], v[212:215], v[18:21]
	v_mfma_f32_16x16x32_bf16 v[14:17], v[180:183], v[220:223], v[14:17]
	v_mfma_f32_16x16x32_bf16 v[10:13], v[194:197], v[220:223], v[10:13]
	v_mfma_f32_16x16x32_bf16 v[6:9], v[180:183], v[228:231], v[6:9]
	v_mfma_f32_16x16x32_bf16 v[2:5], v[194:197], v[228:231], v[2:5]
	v_mfma_f32_16x16x32_bf16 v[30:33], v[184:187], v[208:211], v[30:33]
	v_mfma_f32_16x16x32_bf16 v[26:29], v[200:203], v[208:211], v[26:29]
	v_mfma_f32_16x16x32_bf16 v[22:25], v[184:187], v[216:219], v[22:25]
	v_mfma_f32_16x16x32_bf16 v[18:21], v[200:203], v[216:219], v[18:21]
	v_mfma_f32_16x16x32_bf16 v[14:17], v[184:187], v[224:227], v[14:17]
	v_mfma_f32_16x16x32_bf16 v[10:13], v[200:203], v[224:227], v[10:13]
	v_mfma_f32_16x16x32_bf16 v[6:9], v[184:187], v[232:235], v[6:9]
	v_mfma_f32_16x16x32_bf16 v[2:5], v[200:203], v[232:235], v[2:5]
	s_setprio 0
	s_barrier
	s_add_i32 s55, 0, 0x18000
	v_add_u32_e32 v142, s55, v145
	s_add_i32 s57, 0, 0x1c000
	ds_read_b128 v[130:133], v142
	ds_read_b128 v[168:171], v142 offset:1024
	ds_read_b128 v[172:175], v142 offset:2048
	ds_read_b128 v[176:179], v142 offset:3072
	v_add_u32_e32 v142, s57, v145
	ds_read_b128 v[180:183], v142
	ds_read_b128 v[184:187], v142 offset:1024
	ds_read_b128 v[194:197], v142 offset:2048
	ds_read_b128 v[200:203], v142 offset:3072
	s_add_u32 s10, s10, s24
	s_addc_u32 s11, s11, s25
	s_mov_b32 m0, s94
	v_lshl_add_u64 v[248:249], s[10:11], 0, v[134:135]
	ds_read_b128 v[204:207], v188 offset:32768
	ds_read_b128 v[208:211], v188 offset:33792
	ds_read_b128 v[212:215], v188 offset:34816
	ds_read_b128 v[216:219], v188 offset:35840
	ds_read_b128 v[220:223], v188 offset:36864
	ds_read_b128 v[224:227], v188 offset:37888
	ds_read_b128 v[228:231], v188 offset:38912
	ds_read_b128 v[232:235], v188 offset:39936
	global_load_lds_dwordx4 v[248:249], off
	v_lshl_add_u64 v[248:249], s[10:11], 0, v[138:139]
	s_mov_b32 m0, s95
	s_nop 0
	global_load_lds_dwordx4 v[248:249], off
	s_waitcnt vmcnt(8)
	s_waitcnt lgkmcnt(0)
	s_barrier
	s_setprio 1
	s_waitcnt lgkmcnt(0)
	v_mfma_f32_16x16x32_bf16 v[122:125], v[130:133], v[204:207], v[122:125]
	v_mfma_f32_16x16x32_bf16 v[126:129], v[172:175], v[204:207], v[126:129]
	v_mfma_f32_16x16x32_bf16 v[118:121], v[130:133], v[212:215], v[118:121]
	v_mfma_f32_16x16x32_bf16 v[114:117], v[172:175], v[212:215], v[114:117]
	v_mfma_f32_16x16x32_bf16 v[110:113], v[130:133], v[220:223], v[110:113]
	v_mfma_f32_16x16x32_bf16 v[106:109], v[172:175], v[220:223], v[106:109]
	v_mfma_f32_16x16x32_bf16 v[102:105], v[130:133], v[228:231], v[102:105]
	v_mfma_f32_16x16x32_bf16 v[98:101], v[172:175], v[228:231], v[98:101]
	v_mfma_f32_16x16x32_bf16 v[122:125], v[168:171], v[208:211], v[122:125]
	v_mfma_f32_16x16x32_bf16 v[126:129], v[176:179], v[208:211], v[126:129]
	v_mfma_f32_16x16x32_bf16 v[118:121], v[168:171], v[216:219], v[118:121]
	v_mfma_f32_16x16x32_bf16 v[114:117], v[176:179], v[216:219], v[114:117]
	v_mfma_f32_16x16x32_bf16 v[110:113], v[168:171], v[224:227], v[110:113]
	v_mfma_f32_16x16x32_bf16 v[106:109], v[176:179], v[224:227], v[106:109]
	v_mfma_f32_16x16x32_bf16 v[102:105], v[168:171], v[232:235], v[102:105]
	v_mfma_f32_16x16x32_bf16 v[98:101], v[176:179], v[232:235], v[98:101]
	s_setprio 0
	s_setprio 1
	v_mfma_f32_16x16x32_bf16 v[62:65], v[180:183], v[204:207], v[62:65]
	v_mfma_f32_16x16x32_bf16 v[58:61], v[194:197], v[204:207], v[58:61]
	v_mfma_f32_16x16x32_bf16 v[54:57], v[180:183], v[212:215], v[54:57]
	v_mfma_f32_16x16x32_bf16 v[50:53], v[194:197], v[212:215], v[50:53]
	v_mfma_f32_16x16x32_bf16 v[46:49], v[180:183], v[220:223], v[46:49]
	v_mfma_f32_16x16x32_bf16 v[42:45], v[194:197], v[220:223], v[42:45]
	v_mfma_f32_16x16x32_bf16 v[38:41], v[180:183], v[228:231], v[38:41]
	v_mfma_f32_16x16x32_bf16 v[34:37], v[194:197], v[228:231], v[34:37]
	v_mfma_f32_16x16x32_bf16 v[62:65], v[184:187], v[208:211], v[62:65]
	v_mfma_f32_16x16x32_bf16 v[58:61], v[200:203], v[208:211], v[58:61]
	v_mfma_f32_16x16x32_bf16 v[54:57], v[184:187], v[216:219], v[54:57]
	v_mfma_f32_16x16x32_bf16 v[50:53], v[200:203], v[216:219], v[50:53]
	v_mfma_f32_16x16x32_bf16 v[46:49], v[184:187], v[224:227], v[46:49]
	v_mfma_f32_16x16x32_bf16 v[42:45], v[200:203], v[224:227], v[42:45]
	v_mfma_f32_16x16x32_bf16 v[38:41], v[184:187], v[232:235], v[38:41]
	v_mfma_f32_16x16x32_bf16 v[34:37], v[200:203], v[232:235], v[34:37]
	s_setprio 0
	s_barrier
	s_add_i32 s10, s55, s93
	v_lshl_add_u64 v[236:237], v[236:237], 0, s[30:31]
	s_mov_b32 m0, s10
	ds_read_b128 v[204:207], v188 offset:49152
	ds_read_b128 v[208:211], v188 offset:50176
	ds_read_b128 v[212:215], v188 offset:51200
	ds_read_b128 v[216:219], v188 offset:52224
	ds_read_b128 v[220:223], v188 offset:53248
	ds_read_b128 v[224:227], v188 offset:54272
	ds_read_b128 v[228:231], v188 offset:55296
	ds_read_b128 v[232:235], v188 offset:56320
	global_load_lds_dwordx4 v[236:237], off
	v_lshl_add_u64 v[236:237], v[238:239], 0, s[30:31]
	s_add_i32 m0, s10, 0x2000
	s_add_i32 s10, s57, s93
	global_load_lds_dwordx4 v[236:237], off
	v_lshl_add_u64 v[236:237], v[240:241], 0, s[30:31]
	s_mov_b32 m0, s10
	s_nop 0
	global_load_lds_dwordx4 v[236:237], off
	v_lshl_add_u64 v[236:237], v[242:243], 0, s[30:31]
	s_add_i32 m0, s10, 0x2000
	s_nop 0
	global_load_lds_dwordx4 v[236:237], off
	v_lshl_add_u64 v[236:237], v[244:245], 0, s[30:31]
	s_mov_b32 m0, s74
	s_nop 0
	global_load_lds_dwordx4 v[236:237], off
	v_lshl_add_u64 v[236:237], v[246:247], 0, s[30:31]
	s_mov_b32 m0, s75
	s_nop 0
	global_load_lds_dwordx4 v[236:237], off
	s_waitcnt vmcnt(8)
	s_waitcnt lgkmcnt(0)
	s_barrier
	s_setprio 1
	s_waitcnt lgkmcnt(0)
	v_mfma_f32_16x16x32_bf16 v[94:97], v[130:133], v[204:207], v[94:97]
	v_mfma_f32_16x16x32_bf16 v[90:93], v[172:175], v[204:207], v[90:93]
	v_mfma_f32_16x16x32_bf16 v[86:89], v[130:133], v[212:215], v[86:89]
	v_mfma_f32_16x16x32_bf16 v[82:85], v[172:175], v[212:215], v[82:85]
	v_mfma_f32_16x16x32_bf16 v[78:81], v[130:133], v[220:223], v[78:81]
	v_mfma_f32_16x16x32_bf16 v[74:77], v[172:175], v[220:223], v[74:77]
	v_mfma_f32_16x16x32_bf16 v[70:73], v[130:133], v[228:231], v[70:73]
	v_mfma_f32_16x16x32_bf16 v[66:69], v[172:175], v[228:231], v[66:69]
	v_mfma_f32_16x16x32_bf16 v[94:97], v[168:171], v[208:211], v[94:97]
	v_mfma_f32_16x16x32_bf16 v[90:93], v[176:179], v[208:211], v[90:93]
	v_mfma_f32_16x16x32_bf16 v[86:89], v[168:171], v[216:219], v[86:89]
	v_mfma_f32_16x16x32_bf16 v[82:85], v[176:179], v[216:219], v[82:85]
	v_mfma_f32_16x16x32_bf16 v[78:81], v[168:171], v[224:227], v[78:81]
	v_mfma_f32_16x16x32_bf16 v[74:77], v[176:179], v[224:227], v[74:77]
	v_mfma_f32_16x16x32_bf16 v[70:73], v[168:171], v[232:235], v[70:73]
	v_mfma_f32_16x16x32_bf16 v[66:69], v[176:179], v[232:235], v[66:69]
	s_setprio 0
	s_setprio 1
	v_mfma_f32_16x16x32_bf16 v[30:33], v[180:183], v[204:207], v[30:33]
	v_mfma_f32_16x16x32_bf16 v[26:29], v[194:197], v[204:207], v[26:29]
	v_mfma_f32_16x16x32_bf16 v[22:25], v[180:183], v[212:215], v[22:25]
	v_mfma_f32_16x16x32_bf16 v[18:21], v[194:197], v[212:215], v[18:21]
	v_mfma_f32_16x16x32_bf16 v[14:17], v[180:183], v[220:223], v[14:17]
	v_mfma_f32_16x16x32_bf16 v[10:13], v[194:197], v[220:223], v[10:13]
	v_mfma_f32_16x16x32_bf16 v[6:9], v[180:183], v[228:231], v[6:9]
	v_mfma_f32_16x16x32_bf16 v[2:5], v[194:197], v[228:231], v[2:5]
	v_mfma_f32_16x16x32_bf16 v[30:33], v[184:187], v[208:211], v[30:33]
	v_mfma_f32_16x16x32_bf16 v[26:29], v[200:203], v[208:211], v[26:29]
	v_mfma_f32_16x16x32_bf16 v[22:25], v[184:187], v[216:219], v[22:25]
	v_mfma_f32_16x16x32_bf16 v[18:21], v[200:203], v[216:219], v[18:21]
	v_mfma_f32_16x16x32_bf16 v[14:17], v[184:187], v[224:227], v[14:17]
	v_mfma_f32_16x16x32_bf16 v[10:13], v[200:203], v[224:227], v[10:13]
	v_mfma_f32_16x16x32_bf16 v[6:9], v[184:187], v[232:235], v[6:9]
	v_mfma_f32_16x16x32_bf16 v[2:5], v[200:203], v[232:235], v[2:5]
	s_setprio 0
	s_barrier
	s_add_u32 s8, s8, 0x100
	s_addc_u32 s9, s9, 0
	s_add_u32 s15, s15, 0x100
	s_addc_u32 s44, s44, 0
	s_cmp_ge_i32 s45, s22
	s_mov_b32 s10, s45
	s_cbranch_scc0 .LBB0_867

.LBB0_1337:
	ds_read_b128 v[150:153], v172
	ds_read_b128 v[154:157], v172 offset:1024
	ds_read_b128 v[158:161], v172 offset:2048
	ds_read_b128 v[162:165], v172 offset:3072
	ds_read_b128 v[180:183], v173
	ds_read_b128 v[184:187], v173 offset:1024
	ds_read_b128 v[188:191], v173 offset:2048
	ds_read_b128 v[192:195], v173 offset:3072
	s_add_i32 s53, s10, 2
	s_add_u32 s54, s8, 0x80
	s_addc_u32 s11, s9, 0
	s_cmp_eq_u32 s64, s10
	s_cselect_b32 s10, s21, s54
	s_cselect_b32 s11, s2, s11
	s_cselect_b32 s55, s41, s52
	s_cselect_b32 s54, s50, s51
	s_cbranch_scc0 .Lpf_skip_2
	s_getpc_b64 s[98:99]
	s_mov_b32 m0, 0x22800
	v_lshlrev_b32_e32 v196, 7, v0
	global_load_lds_dword v196, s[98:99]
.Lpf_skip_2:
	v_lshl_add_u64 v[196:197], s[8:9], 0, v[146:147]
	s_add_i32 m0, s18, 0xc000
	ds_read_b128 v[200:203], v174
	ds_read_b128 v[204:207], v174 offset:1024
	ds_read_b128 v[208:211], v174 offset:2048
	ds_read_b128 v[212:215], v174 offset:3072
	ds_read_b128 v[216:219], v174 offset:4096
	ds_read_b128 v[220:223], v174 offset:5120
	ds_read_b128 v[224:227], v174 offset:6144
	ds_read_b128 v[228:231], v174 offset:7168
	global_load_lds_dwordx4 v[196:197], off
	v_lshl_add_u64 v[196:197], s[8:9], 0, v[148:149]
	s_add_i32 m0, s18, 0xe000
	s_nop 0
	global_load_lds_dwordx4 v[196:197], off
	s_waitcnt vmcnt(8)
	s_waitcnt lgkmcnt(0)
	s_barrier
	s_setprio 1
	s_waitcnt lgkmcnt(0)
	v_mfma_f32_16x16x32_bf16 v[122:125], v[150:153], v[200:203], v[122:125]
	v_mfma_f32_16x16x32_bf16 v[126:129], v[158:161], v[200:203], v[126:129]
	v_mfma_f32_16x16x32_bf16 v[118:121], v[150:153], v[208:211], v[118:121]
	v_mfma_f32_16x16x32_bf16 v[114:117], v[158:161], v[208:211], v[114:117]
	v_mfma_f32_16x16x32_bf16 v[110:113], v[150:153], v[216:219], v[110:113]
	v_mfma_f32_16x16x32_bf16 v[106:109], v[158:161], v[216:219], v[106:109]
	v_mfma_f32_16x16x32_bf16 v[102:105], v[150:153], v[224:227], v[102:105]
	v_mfma_f32_16x16x32_bf16 v[98:101], v[158:161], v[224:227], v[98:101]
	v_mfma_f32_16x16x32_bf16 v[122:125], v[154:157], v[204:207], v[122:125]
	v_mfma_f32_16x16x32_bf16 v[126:129], v[162:165], v[204:207], v[126:129]
	v_mfma_f32_16x16x32_bf16 v[118:121], v[154:157], v[212:215], v[118:121]
	v_mfma_f32_16x16x32_bf16 v[114:117], v[162:165], v[212:215], v[114:117]
	v_mfma_f32_16x16x32_bf16 v[110:113], v[154:157], v[220:223], v[110:113]
	v_mfma_f32_16x16x32_bf16 v[106:109], v[162:165], v[220:223], v[106:109]
	v_mfma_f32_16x16x32_bf16 v[102:105], v[154:157], v[228:231], v[102:105]
	v_mfma_f32_16x16x32_bf16 v[98:101], v[162:165], v[228:231], v[98:101]
	s_setprio 0
	s_setprio 1
	v_mfma_f32_16x16x32_bf16 v[62:65], v[180:183], v[200:203], v[62:65]
	v_mfma_f32_16x16x32_bf16 v[58:61], v[188:191], v[200:203], v[58:61]
	v_mfma_f32_16x16x32_bf16 v[54:57], v[180:183], v[208:211], v[54:57]
	v_mfma_f32_16x16x32_bf16 v[50:53], v[188:191], v[208:211], v[50:53]
	v_mfma_f32_16x16x32_bf16 v[46:49], v[180:183], v[216:219], v[46:49]
	v_mfma_f32_16x16x32_bf16 v[42:45], v[188:191], v[216:219], v[42:45]
	v_mfma_f32_16x16x32_bf16 v[38:41], v[180:183], v[224:227], v[38:41]
	v_mfma_f32_16x16x32_bf16 v[34:37], v[188:191], v[224:227], v[34:37]
	v_mfma_f32_16x16x32_bf16 v[62:65], v[184:187], v[204:207], v[62:65]
	v_mfma_f32_16x16x32_bf16 v[58:61], v[192:195], v[204:207], v[58:61]
	v_mfma_f32_16x16x32_bf16 v[54:57], v[184:187], v[212:215], v[54:57]
	v_mfma_f32_16x16x32_bf16 v[50:53], v[192:195], v[212:215], v[50:53]
	v_mfma_f32_16x16x32_bf16 v[46:49], v[184:187], v[220:223], v[46:49]
	v_mfma_f32_16x16x32_bf16 v[42:45], v[192:195], v[220:223], v[42:45]
	v_mfma_f32_16x16x32_bf16 v[38:41], v[184:187], v[228:231], v[38:41]
	v_mfma_f32_16x16x32_bf16 v[34:37], v[192:195], v[228:231], v[34:37]
	s_setprio 0
	s_barrier
	s_add_i32 s84, s68, s16
	v_lshl_add_u64 v[196:197], s[54:55], 0, v[132:133]
	s_mov_b32 m0, s84
	ds_read_b128 v[200:203], v174 offset:16384
	ds_read_b128 v[204:207], v174 offset:17408
	ds_read_b128 v[208:211], v174 offset:18432
	ds_read_b128 v[212:215], v174 offset:19456
	ds_read_b128 v[216:219], v174 offset:20480
	ds_read_b128 v[220:223], v174 offset:21504
	ds_read_b128 v[224:227], v174 offset:22528
	ds_read_b128 v[228:231], v174 offset:23552
	global_load_lds_dwordx4 v[196:197], off
	s_add_i32 m0, s84, 0x2000
	v_lshl_add_u64 v[232:233], s[54:55], 0, v[136:137]
	s_add_u32 s54, s54, s12
	s_addc_u32 s55, s55, s13
	s_add_i32 s84, s69, s16
	global_load_lds_dwordx4 v[232:233], off
	v_lshl_add_u64 v[234:235], s[54:55], 0, v[132:133]
	s_mov_b32 m0, s84
	v_lshl_add_u64 v[236:237], s[54:55], 0, v[136:137]
	global_load_lds_dwordx4 v[234:235], off
	s_add_i32 m0, s84, 0x2000
	v_lshl_add_u64 v[238:239], s[10:11], 0, v[130:131]
	global_load_lds_dwordx4 v[236:237], off
	s_mov_b32 m0, s18
	v_lshl_add_u64 v[240:241], s[10:11], 0, v[134:135]
	global_load_lds_dwordx4 v[238:239], off
	s_mov_b32 m0, s19
	s_nop 0
	global_load_lds_dwordx4 v[240:241], off
	s_waitcnt vmcnt(8)
	s_waitcnt lgkmcnt(0)
	s_barrier
	s_setprio 1
	s_waitcnt lgkmcnt(0)
	v_mfma_f32_16x16x32_bf16 v[94:97], v[150:153], v[200:203], v[94:97]
	v_mfma_f32_16x16x32_bf16 v[90:93], v[158:161], v[200:203], v[90:93]
	v_mfma_f32_16x16x32_bf16 v[86:89], v[150:153], v[208:211], v[86:89]
	v_mfma_f32_16x16x32_bf16 v[82:85], v[158:161], v[208:211], v[82:85]
	v_mfma_f32_16x16x32_bf16 v[78:81], v[150:153], v[216:219], v[78:81]
	v_mfma_f32_16x16x32_bf16 v[74:77], v[158:161], v[216:219], v[74:77]
	v_mfma_f32_16x16x32_bf16 v[70:73], v[150:153], v[224:227], v[70:73]
	v_mfma_f32_16x16x32_bf16 v[66:69], v[158:161], v[224:227], v[66:69]
	v_mfma_f32_16x16x32_bf16 v[94:97], v[154:157], v[204:207], v[94:97]
	v_mfma_f32_16x16x32_bf16 v[90:93], v[162:165], v[204:207], v[90:93]
	v_mfma_f32_16x16x32_bf16 v[86:89], v[154:157], v[212:215], v[86:89]
	v_mfma_f32_16x16x32_bf16 v[82:85], v[162:165], v[212:215], v[82:85]
	v_mfma_f32_16x16x32_bf16 v[78:81], v[154:157], v[220:223], v[78:81]
	v_mfma_f32_16x16x32_bf16 v[74:77], v[162:165], v[220:223], v[74:77]
	v_mfma_f32_16x16x32_bf16 v[70:73], v[154:157], v[228:231], v[70:73]
	v_mfma_f32_16x16x32_bf16 v[66:69], v[162:165], v[228:231], v[66:69]
	s_setprio 0
	s_setprio 1
	v_mfma_f32_16x16x32_bf16 v[30:33], v[180:183], v[200:203], v[30:33]
	v_mfma_f32_16x16x32_bf16 v[26:29], v[188:191], v[200:203], v[26:29]
	v_mfma_f32_16x16x32_bf16 v[22:25], v[180:183], v[208:211], v[22:25]
	v_mfma_f32_16x16x32_bf16 v[18:21], v[188:191], v[208:211], v[18:21]
	v_mfma_f32_16x16x32_bf16 v[14:17], v[180:183], v[216:219], v[14:17]
	v_mfma_f32_16x16x32_bf16 v[10:13], v[188:191], v[216:219], v[10:13]
	v_mfma_f32_16x16x32_bf16 v[6:9], v[180:183], v[224:227], v[6:9]
	v_mfma_f32_16x16x32_bf16 v[2:5], v[188:191], v[224:227], v[2:5]
	v_mfma_f32_16x16x32_bf16 v[30:33], v[184:187], v[204:207], v[30:33]
	v_mfma_f32_16x16x32_bf16 v[26:29], v[192:195], v[204:207], v[26:29]
	v_mfma_f32_16x16x32_bf16 v[22:25], v[184:187], v[212:215], v[22:25]
	v_mfma_f32_16x16x32_bf16 v[18:21], v[192:195], v[212:215], v[18:21]
	v_mfma_f32_16x16x32_bf16 v[14:17], v[184:187], v[220:223], v[14:17]
	v_mfma_f32_16x16x32_bf16 v[10:13], v[192:195], v[220:223], v[10:13]
	v_mfma_f32_16x16x32_bf16 v[6:9], v[184:187], v[228:231], v[6:9]
	v_mfma_f32_16x16x32_bf16 v[2:5], v[192:195], v[228:231], v[2:5]
	s_setprio 0
	s_barrier
	s_add_i32 s54, 0, 0x18000
	v_add_u32_e32 v138, s54, v166
	s_add_i32 s55, 0, 0x1c000
	ds_read_b128 v[150:153], v138
	ds_read_b128 v[154:157], v138 offset:1024
	ds_read_b128 v[158:161], v138 offset:2048
	ds_read_b128 v[162:165], v138 offset:3072
	v_add_u32_e32 v138, s55, v166
	ds_read_b128 v[180:183], v138
	ds_read_b128 v[184:187], v138 offset:1024
	ds_read_b128 v[188:191], v138 offset:2048
	ds_read_b128 v[192:195], v138 offset:3072
	s_add_u32 s10, s10, s12
	s_addc_u32 s11, s11, s13
	s_mov_b32 m0, s33
	v_lshl_add_u64 v[242:243], s[10:11], 0, v[130:131]
	ds_read_b128 v[200:203], v174 offset:32768
	ds_read_b128 v[204:207], v174 offset:33792
	ds_read_b128 v[208:211], v174 offset:34816
	ds_read_b128 v[212:215], v174 offset:35840
	ds_read_b128 v[216:219], v174 offset:36864
	ds_read_b128 v[220:223], v174 offset:37888
	ds_read_b128 v[224:227], v174 offset:38912
	ds_read_b128 v[228:231], v174 offset:39936
	global_load_lds_dwordx4 v[242:243], off
	v_lshl_add_u64 v[242:243], s[10:11], 0, v[134:135]
	s_mov_b32 m0, s39
	s_nop 0
	global_load_lds_dwordx4 v[242:243], off
	s_waitcnt vmcnt(8)
	s_waitcnt lgkmcnt(0)
	s_barrier
	s_setprio 1
	s_waitcnt lgkmcnt(0)
	v_mfma_f32_16x16x32_bf16 v[122:125], v[150:153], v[200:203], v[122:125]
	v_mfma_f32_16x16x32_bf16 v[126:129], v[158:161], v[200:203], v[126:129]
	v_mfma_f32_16x16x32_bf16 v[118:121], v[150:153], v[208:211], v[118:121]
	v_mfma_f32_16x16x32_bf16 v[114:117], v[158:161], v[208:211], v[114:117]
	v_mfma_f32_16x16x32_bf16 v[110:113], v[150:153], v[216:219], v[110:113]
	v_mfma_f32_16x16x32_bf16 v[106:109], v[158:161], v[216:219], v[106:109]
	v_mfma_f32_16x16x32_bf16 v[102:105], v[150:153], v[224:227], v[102:105]
	v_mfma_f32_16x16x32_bf16 v[98:101], v[158:161], v[224:227], v[98:101]
	v_mfma_f32_16x16x32_bf16 v[122:125], v[154:157], v[204:207], v[122:125]
	v_mfma_f32_16x16x32_bf16 v[126:129], v[162:165], v[204:207], v[126:129]
	v_mfma_f32_16x16x32_bf16 v[118:121], v[154:157], v[212:215], v[118:121]
	v_mfma_f32_16x16x32_bf16 v[114:117], v[162:165], v[212:215], v[114:117]
	v_mfma_f32_16x16x32_bf16 v[110:113], v[154:157], v[220:223], v[110:113]
	v_mfma_f32_16x16x32_bf16 v[106:109], v[162:165], v[220:223], v[106:109]
	v_mfma_f32_16x16x32_bf16 v[102:105], v[154:157], v[228:231], v[102:105]
	v_mfma_f32_16x16x32_bf16 v[98:101], v[162:165], v[228:231], v[98:101]
	s_setprio 0
	s_setprio 1
	v_mfma_f32_16x16x32_bf16 v[62:65], v[180:183], v[200:203], v[62:65]
	v_mfma_f32_16x16x32_bf16 v[58:61], v[188:191], v[200:203], v[58:61]
	v_mfma_f32_16x16x32_bf16 v[54:57], v[180:183], v[208:211], v[54:57]
	v_mfma_f32_16x16x32_bf16 v[50:53], v[188:191], v[208:211], v[50:53]
	v_mfma_f32_16x16x32_bf16 v[46:49], v[180:183], v[216:219], v[46:49]
	v_mfma_f32_16x16x32_bf16 v[42:45], v[188:191], v[216:219], v[42:45]
	v_mfma_f32_16x16x32_bf16 v[38:41], v[180:183], v[224:227], v[38:41]
	v_mfma_f32_16x16x32_bf16 v[34:37], v[188:191], v[224:227], v[34:37]
	v_mfma_f32_16x16x32_bf16 v[62:65], v[184:187], v[204:207], v[62:65]
	v_mfma_f32_16x16x32_bf16 v[58:61], v[192:195], v[204:207], v[58:61]
	v_mfma_f32_16x16x32_bf16 v[54:57], v[184:187], v[212:215], v[54:57]
	v_mfma_f32_16x16x32_bf16 v[50:53], v[192:195], v[212:215], v[50:53]
	v_mfma_f32_16x16x32_bf16 v[46:49], v[184:187], v[220:223], v[46:49]
	v_mfma_f32_16x16x32_bf16 v[42:45], v[192:195], v[220:223], v[42:45]
	v_mfma_f32_16x16x32_bf16 v[38:41], v[184:187], v[228:231], v[38:41]
	v_mfma_f32_16x16x32_bf16 v[34:37], v[192:195], v[228:231], v[34:37]
	s_setprio 0
	s_barrier
	s_add_i32 s10, s54, s16
	v_lshl_add_u64 v[196:197], v[196:197], 0, s[22:23]
	s_mov_b32 m0, s10
	ds_read_b128 v[200:203], v174 offset:49152
	ds_read_b128 v[204:207], v174 offset:50176
	ds_read_b128 v[208:211], v174 offset:51200
	ds_read_b128 v[212:215], v174 offset:52224
	ds_read_b128 v[216:219], v174 offset:53248
	ds_read_b128 v[220:223], v174 offset:54272
	ds_read_b128 v[224:227], v174 offset:55296
	ds_read_b128 v[228:231], v174 offset:56320
	global_load_lds_dwordx4 v[196:197], off
	v_lshl_add_u64 v[196:197], v[232:233], 0, s[22:23]
	s_add_i32 m0, s10, 0x2000
	s_add_i32 s10, s55, s16
	global_load_lds_dwordx4 v[196:197], off
	v_lshl_add_u64 v[196:197], v[234:235], 0, s[22:23]
	s_mov_b32 m0, s10
	s_nop 0
	global_load_lds_dwordx4 v[196:197], off
	v_lshl_add_u64 v[196:197], v[236:237], 0, s[22:23]
	s_add_i32 m0, s10, 0x2000
	s_nop 0
	global_load_lds_dwordx4 v[196:197], off
	v_lshl_add_u64 v[196:197], v[238:239], 0, s[22:23]
	s_mov_b32 m0, s57
	s_nop 0
	global_load_lds_dwordx4 v[196:197], off
	v_lshl_add_u64 v[196:197], v[240:241], 0, s[22:23]
	s_mov_b32 m0, s58
	s_nop 0
	global_load_lds_dwordx4 v[196:197], off
	s_waitcnt vmcnt(8)
	s_waitcnt lgkmcnt(0)
	s_barrier
	s_setprio 1
	s_waitcnt lgkmcnt(0)
	v_mfma_f32_16x16x32_bf16 v[94:97], v[150:153], v[200:203], v[94:97]
	v_mfma_f32_16x16x32_bf16 v[90:93], v[158:161], v[200:203], v[90:93]
	v_mfma_f32_16x16x32_bf16 v[86:89], v[150:153], v[208:211], v[86:89]
	v_mfma_f32_16x16x32_bf16 v[82:85], v[158:161], v[208:211], v[82:85]
	v_mfma_f32_16x16x32_bf16 v[78:81], v[150:153], v[216:219], v[78:81]
	v_mfma_f32_16x16x32_bf16 v[74:77], v[158:161], v[216:219], v[74:77]
	v_mfma_f32_16x16x32_bf16 v[70:73], v[150:153], v[224:227], v[70:73]
	v_mfma_f32_16x16x32_bf16 v[66:69], v[158:161], v[224:227], v[66:69]
	v_mfma_f32_16x16x32_bf16 v[94:97], v[154:157], v[204:207], v[94:97]
	v_mfma_f32_16x16x32_bf16 v[90:93], v[162:165], v[204:207], v[90:93]
	v_mfma_f32_16x16x32_bf16 v[86:89], v[154:157], v[212:215], v[86:89]
	v_mfma_f32_16x16x32_bf16 v[82:85], v[162:165], v[212:215], v[82:85]
	v_mfma_f32_16x16x32_bf16 v[78:81], v[154:157], v[220:223], v[78:81]
	v_mfma_f32_16x16x32_bf16 v[74:77], v[162:165], v[220:223], v[74:77]
	v_mfma_f32_16x16x32_bf16 v[70:73], v[154:157], v[228:231], v[70:73]
	v_mfma_f32_16x16x32_bf16 v[66:69], v[162:165], v[228:231], v[66:69]
	s_setprio 0
	s_setprio 1
	v_mfma_f32_16x16x32_bf16 v[30:33], v[180:183], v[200:203], v[30:33]
	v_mfma_f32_16x16x32_bf16 v[26:29], v[188:191], v[200:203], v[26:29]
	v_mfma_f32_16x16x32_bf16 v[22:25], v[180:183], v[208:211], v[22:25]
	v_mfma_f32_16x16x32_bf16 v[18:21], v[188:191], v[208:211], v[18:21]
	v_mfma_f32_16x16x32_bf16 v[14:17], v[180:183], v[216:219], v[14:17]
	v_mfma_f32_16x16x32_bf16 v[10:13], v[188:191], v[216:219], v[10:13]
	v_mfma_f32_16x16x32_bf16 v[6:9], v[180:183], v[224:227], v[6:9]
	v_mfma_f32_16x16x32_bf16 v[2:5], v[188:191], v[224:227], v[2:5]
	v_mfma_f32_16x16x32_bf16 v[30:33], v[184:187], v[204:207], v[30:33]
	v_mfma_f32_16x16x32_bf16 v[26:29], v[192:195], v[204:207], v[26:29]
	v_mfma_f32_16x16x32_bf16 v[22:25], v[184:187], v[212:215], v[22:25]
	v_mfma_f32_16x16x32_bf16 v[18:21], v[192:195], v[212:215], v[18:21]
	v_mfma_f32_16x16x32_bf16 v[14:17], v[184:187], v[220:223], v[14:17]
	v_mfma_f32_16x16x32_bf16 v[10:13], v[192:195], v[220:223], v[10:13]
	v_mfma_f32_16x16x32_bf16 v[6:9], v[184:187], v[228:231], v[6:9]
	v_mfma_f32_16x16x32_bf16 v[2:5], v[192:195], v[228:231], v[2:5]
	s_setprio 0
	s_barrier
	s_add_u32 s8, s8, 0x100
	s_addc_u32 s9, s9, 0
	s_add_u32 s51, s51, 0x100
	s_addc_u32 s52, s52, 0
	s_cmp_ge_i32 s53, s61
	s_mov_b32 s10, s53
	s_cbranch_scc0 .LBB0_1337

.LBB0_1556:
	ds_read_b128 v[150:153], v172
	ds_read_b128 v[154:157], v172 offset:1024
	ds_read_b128 v[158:161], v172 offset:2048
	ds_read_b128 v[162:165], v172 offset:3072
	ds_read_b128 v[180:183], v173
	ds_read_b128 v[184:187], v173 offset:1024
	ds_read_b128 v[188:191], v173 offset:2048
	ds_read_b128 v[192:195], v173 offset:3072
	s_add_i32 s48, s8, 2
	s_add_u32 s49, s6, 0x80
	s_addc_u32 s9, s7, 0
	s_cmp_eq_u32 s64, s8
	s_cselect_b32 s8, s31, s49
	s_cselect_b32 s9, s3, s9
	s_cselect_b32 s85, s35, s47
	s_cselect_b32 s84, s45, s46
	s_cbranch_scc0 .Lpf_skip_3
	s_getpc_b64 s[98:99]
	s_mov_b32 m0, 0x22800
	v_lshlrev_b32_e32 v196, 7, v0
	global_load_lds_dword v196, s[98:99]
.Lpf_skip_3:
	v_lshl_add_u64 v[196:197], s[6:7], 0, v[146:147]
	s_add_i32 m0, s29, 0xc000
	ds_read_b128 v[200:203], v174
	ds_read_b128 v[204:207], v174 offset:1024
	ds_read_b128 v[208:211], v174 offset:2048
	ds_read_b128 v[212:215], v174 offset:3072
	ds_read_b128 v[216:219], v174 offset:4096
	ds_read_b128 v[220:223], v174 offset:5120
	ds_read_b128 v[224:227], v174 offset:6144
	ds_read_b128 v[228:231], v174 offset:7168
	global_load_lds_dwordx4 v[196:197], off
	v_lshl_add_u64 v[196:197], s[6:7], 0, v[148:149]
	s_add_i32 m0, s29, 0xe000
	s_nop 0
	global_load_lds_dwordx4 v[196:197], off
	s_waitcnt vmcnt(8)
	s_waitcnt lgkmcnt(0)
	s_barrier
	s_setprio 1
	s_waitcnt lgkmcnt(0)
	v_mfma_f32_16x16x32_bf16 v[122:125], v[150:153], v[200:203], v[122:125]
	v_mfma_f32_16x16x32_bf16 v[126:129], v[158:161], v[200:203], v[126:129]
	v_mfma_f32_16x16x32_bf16 v[118:121], v[150:153], v[208:211], v[118:121]
	v_mfma_f32_16x16x32_bf16 v[114:117], v[158:161], v[208:211], v[114:117]
	v_mfma_f32_16x16x32_bf16 v[110:113], v[150:153], v[216:219], v[110:113]
	v_mfma_f32_16x16x32_bf16 v[106:109], v[158:161], v[216:219], v[106:109]
	v_mfma_f32_16x16x32_bf16 v[102:105], v[150:153], v[224:227], v[102:105]
	v_mfma_f32_16x16x32_bf16 v[98:101], v[158:161], v[224:227], v[98:101]
	v_mfma_f32_16x16x32_bf16 v[122:125], v[154:157], v[204:207], v[122:125]
	v_mfma_f32_16x16x32_bf16 v[126:129], v[162:165], v[204:207], v[126:129]
	v_mfma_f32_16x16x32_bf16 v[118:121], v[154:157], v[212:215], v[118:121]
	v_mfma_f32_16x16x32_bf16 v[114:117], v[162:165], v[212:215], v[114:117]
	v_mfma_f32_16x16x32_bf16 v[110:113], v[154:157], v[220:223], v[110:113]
	v_mfma_f32_16x16x32_bf16 v[106:109], v[162:165], v[220:223], v[106:109]
	v_mfma_f32_16x16x32_bf16 v[102:105], v[154:157], v[228:231], v[102:105]
	v_mfma_f32_16x16x32_bf16 v[98:101], v[162:165], v[228:231], v[98:101]
	s_setprio 0
	s_setprio 1
	v_mfma_f32_16x16x32_bf16 v[62:65], v[180:183], v[200:203], v[62:65]
	v_mfma_f32_16x16x32_bf16 v[58:61], v[188:191], v[200:203], v[58:61]
	v_mfma_f32_16x16x32_bf16 v[54:57], v[180:183], v[208:211], v[54:57]
	v_mfma_f32_16x16x32_bf16 v[50:53], v[188:191], v[208:211], v[50:53]
	v_mfma_f32_16x16x32_bf16 v[46:49], v[180:183], v[216:219], v[46:49]
	v_mfma_f32_16x16x32_bf16 v[42:45], v[188:191], v[216:219], v[42:45]
	v_mfma_f32_16x16x32_bf16 v[38:41], v[180:183], v[224:227], v[38:41]
	v_mfma_f32_16x16x32_bf16 v[34:37], v[188:191], v[224:227], v[34:37]
	v_mfma_f32_16x16x32_bf16 v[62:65], v[184:187], v[204:207], v[62:65]
	v_mfma_f32_16x16x32_bf16 v[58:61], v[192:195], v[204:207], v[58:61]
	v_mfma_f32_16x16x32_bf16 v[54:57], v[184:187], v[212:215], v[54:57]
	v_mfma_f32_16x16x32_bf16 v[50:53], v[192:195], v[212:215], v[50:53]
	v_mfma_f32_16x16x32_bf16 v[46:49], v[184:187], v[220:223], v[46:49]
	v_mfma_f32_16x16x32_bf16 v[42:45], v[192:195], v[220:223], v[42:45]
	v_mfma_f32_16x16x32_bf16 v[38:41], v[184:187], v[228:231], v[38:41]
	v_mfma_f32_16x16x32_bf16 v[34:37], v[192:195], v[228:231], v[34:37]
	s_setprio 0
	s_barrier
	s_add_i32 s49, s68, s51
	v_lshl_add_u64 v[196:197], s[84:85], 0, v[132:133]
	s_mov_b32 m0, s49
	ds_read_b128 v[200:203], v174 offset:16384
	ds_read_b128 v[204:207], v174 offset:17408
	ds_read_b128 v[208:211], v174 offset:18432
	ds_read_b128 v[212:215], v174 offset:19456
	ds_read_b128 v[216:219], v174 offset:20480
	ds_read_b128 v[220:223], v174 offset:21504
	ds_read_b128 v[224:227], v174 offset:22528
	ds_read_b128 v[228:231], v174 offset:23552
	global_load_lds_dwordx4 v[196:197], off
	s_add_i32 m0, s49, 0x2000
	v_lshl_add_u64 v[232:233], s[84:85], 0, v[136:137]
	s_add_u32 s84, s84, s10
	s_addc_u32 s85, s85, s11
	s_add_i32 s49, s69, s51
	global_load_lds_dwordx4 v[232:233], off
	v_lshl_add_u64 v[234:235], s[84:85], 0, v[132:133]
	s_mov_b32 m0, s49
	v_lshl_add_u64 v[236:237], s[84:85], 0, v[136:137]
	global_load_lds_dwordx4 v[234:235], off
	s_add_i32 m0, s49, 0x2000
	v_lshl_add_u64 v[238:239], s[8:9], 0, v[130:131]
	global_load_lds_dwordx4 v[236:237], off
	s_mov_b32 m0, s29
	v_lshl_add_u64 v[240:241], s[8:9], 0, v[134:135]
	global_load_lds_dwordx4 v[238:239], off
	s_mov_b32 m0, s43
	s_nop 0
	global_load_lds_dwordx4 v[240:241], off
	s_waitcnt vmcnt(8)
	s_waitcnt lgkmcnt(0)
	s_barrier
	s_setprio 1
	s_waitcnt lgkmcnt(0)
	v_mfma_f32_16x16x32_bf16 v[94:97], v[150:153], v[200:203], v[94:97]
	v_mfma_f32_16x16x32_bf16 v[90:93], v[158:161], v[200:203], v[90:93]
	v_mfma_f32_16x16x32_bf16 v[86:89], v[150:153], v[208:211], v[86:89]
	v_mfma_f32_16x16x32_bf16 v[82:85], v[158:161], v[208:211], v[82:85]
	v_mfma_f32_16x16x32_bf16 v[78:81], v[150:153], v[216:219], v[78:81]
	v_mfma_f32_16x16x32_bf16 v[74:77], v[158:161], v[216:219], v[74:77]
	v_mfma_f32_16x16x32_bf16 v[70:73], v[150:153], v[224:227], v[70:73]
	v_mfma_f32_16x16x32_bf16 v[66:69], v[158:161], v[224:227], v[66:69]
	v_mfma_f32_16x16x32_bf16 v[94:97], v[154:157], v[204:207], v[94:97]
	v_mfma_f32_16x16x32_bf16 v[90:93], v[162:165], v[204:207], v[90:93]
	v_mfma_f32_16x16x32_bf16 v[86:89], v[154:157], v[212:215], v[86:89]
	v_mfma_f32_16x16x32_bf16 v[82:85], v[162:165], v[212:215], v[82:85]
	v_mfma_f32_16x16x32_bf16 v[78:81], v[154:157], v[220:223], v[78:81]
	v_mfma_f32_16x16x32_bf16 v[74:77], v[162:165], v[220:223], v[74:77]
	v_mfma_f32_16x16x32_bf16 v[70:73], v[154:157], v[228:231], v[70:73]
	v_mfma_f32_16x16x32_bf16 v[66:69], v[162:165], v[228:231], v[66:69]
	s_setprio 0
	s_setprio 1
	v_mfma_f32_16x16x32_bf16 v[30:33], v[180:183], v[200:203], v[30:33]
	v_mfma_f32_16x16x32_bf16 v[26:29], v[188:191], v[200:203], v[26:29]
	v_mfma_f32_16x16x32_bf16 v[22:25], v[180:183], v[208:211], v[22:25]
	v_mfma_f32_16x16x32_bf16 v[18:21], v[188:191], v[208:211], v[18:21]
	v_mfma_f32_16x16x32_bf16 v[14:17], v[180:183], v[216:219], v[14:17]
	v_mfma_f32_16x16x32_bf16 v[10:13], v[188:191], v[216:219], v[10:13]
	v_mfma_f32_16x16x32_bf16 v[6:9], v[180:183], v[224:227], v[6:9]
	v_mfma_f32_16x16x32_bf16 v[2:5], v[188:191], v[224:227], v[2:5]
	v_mfma_f32_16x16x32_bf16 v[30:33], v[184:187], v[204:207], v[30:33]
	v_mfma_f32_16x16x32_bf16 v[26:29], v[192:195], v[204:207], v[26:29]
	v_mfma_f32_16x16x32_bf16 v[22:25], v[184:187], v[212:215], v[22:25]
	v_mfma_f32_16x16x32_bf16 v[18:21], v[192:195], v[212:215], v[18:21]
	v_mfma_f32_16x16x32_bf16 v[14:17], v[184:187], v[220:223], v[14:17]
	v_mfma_f32_16x16x32_bf16 v[10:13], v[192:195], v[220:223], v[10:13]
	v_mfma_f32_16x16x32_bf16 v[6:9], v[184:187], v[228:231], v[6:9]
	v_mfma_f32_16x16x32_bf16 v[2:5], v[192:195], v[228:231], v[2:5]
	s_setprio 0
	s_barrier
	s_add_i32 s49, 0, 0x18000
	v_add_u32_e32 v138, s49, v166
	s_add_i32 s84, 0, 0x1c000
	ds_read_b128 v[150:153], v138
	ds_read_b128 v[154:157], v138 offset:1024
	ds_read_b128 v[158:161], v138 offset:2048
	ds_read_b128 v[162:165], v138 offset:3072
	v_add_u32_e32 v138, s84, v166
	ds_read_b128 v[180:183], v138
	ds_read_b128 v[184:187], v138 offset:1024
	ds_read_b128 v[188:191], v138 offset:2048
	ds_read_b128 v[192:195], v138 offset:3072
	s_add_u32 s8, s8, s10
	s_addc_u32 s9, s9, s11
	s_mov_b32 m0, s53
	v_lshl_add_u64 v[242:243], s[8:9], 0, v[130:131]
	ds_read_b128 v[200:203], v174 offset:32768
	ds_read_b128 v[204:207], v174 offset:33792
	ds_read_b128 v[208:211], v174 offset:34816
	ds_read_b128 v[212:215], v174 offset:35840
	ds_read_b128 v[216:219], v174 offset:36864
	ds_read_b128 v[220:223], v174 offset:37888
	ds_read_b128 v[224:227], v174 offset:38912
	ds_read_b128 v[228:231], v174 offset:39936
	global_load_lds_dwordx4 v[242:243], off
	v_lshl_add_u64 v[242:243], s[8:9], 0, v[134:135]
	s_mov_b32 m0, s54
	s_nop 0
	global_load_lds_dwordx4 v[242:243], off
	s_waitcnt vmcnt(8)
	s_waitcnt lgkmcnt(0)
	s_barrier
	s_setprio 1
	s_waitcnt lgkmcnt(0)
	v_mfma_f32_16x16x32_bf16 v[122:125], v[150:153], v[200:203], v[122:125]
	v_mfma_f32_16x16x32_bf16 v[126:129], v[158:161], v[200:203], v[126:129]
	v_mfma_f32_16x16x32_bf16 v[118:121], v[150:153], v[208:211], v[118:121]
	v_mfma_f32_16x16x32_bf16 v[114:117], v[158:161], v[208:211], v[114:117]
	v_mfma_f32_16x16x32_bf16 v[110:113], v[150:153], v[216:219], v[110:113]
	v_mfma_f32_16x16x32_bf16 v[106:109], v[158:161], v[216:219], v[106:109]
	v_mfma_f32_16x16x32_bf16 v[102:105], v[150:153], v[224:227], v[102:105]
	v_mfma_f32_16x16x32_bf16 v[98:101], v[158:161], v[224:227], v[98:101]
	v_mfma_f32_16x16x32_bf16 v[122:125], v[154:157], v[204:207], v[122:125]
	v_mfma_f32_16x16x32_bf16 v[126:129], v[162:165], v[204:207], v[126:129]
	v_mfma_f32_16x16x32_bf16 v[118:121], v[154:157], v[212:215], v[118:121]
	v_mfma_f32_16x16x32_bf16 v[114:117], v[162:165], v[212:215], v[114:117]
	v_mfma_f32_16x16x32_bf16 v[110:113], v[154:157], v[220:223], v[110:113]
	v_mfma_f32_16x16x32_bf16 v[106:109], v[162:165], v[220:223], v[106:109]
	v_mfma_f32_16x16x32_bf16 v[102:105], v[154:157], v[228:231], v[102:105]
	v_mfma_f32_16x16x32_bf16 v[98:101], v[162:165], v[228:231], v[98:101]
	s_setprio 0
	s_setprio 1
	v_mfma_f32_16x16x32_bf16 v[62:65], v[180:183], v[200:203], v[62:65]
	v_mfma_f32_16x16x32_bf16 v[58:61], v[188:191], v[200:203], v[58:61]
	v_mfma_f32_16x16x32_bf16 v[54:57], v[180:183], v[208:211], v[54:57]
	v_mfma_f32_16x16x32_bf16 v[50:53], v[188:191], v[208:211], v[50:53]
	v_mfma_f32_16x16x32_bf16 v[46:49], v[180:183], v[216:219], v[46:49]
	v_mfma_f32_16x16x32_bf16 v[42:45], v[188:191], v[216:219], v[42:45]
	v_mfma_f32_16x16x32_bf16 v[38:41], v[180:183], v[224:227], v[38:41]
	v_mfma_f32_16x16x32_bf16 v[34:37], v[188:191], v[224:227], v[34:37]
	v_mfma_f32_16x16x32_bf16 v[62:65], v[184:187], v[204:207], v[62:65]
	v_mfma_f32_16x16x32_bf16 v[58:61], v[192:195], v[204:207], v[58:61]
	v_mfma_f32_16x16x32_bf16 v[54:57], v[184:187], v[212:215], v[54:57]
	v_mfma_f32_16x16x32_bf16 v[50:53], v[192:195], v[212:215], v[50:53]
	v_mfma_f32_16x16x32_bf16 v[46:49], v[184:187], v[220:223], v[46:49]
	v_mfma_f32_16x16x32_bf16 v[42:45], v[192:195], v[220:223], v[42:45]
	v_mfma_f32_16x16x32_bf16 v[38:41], v[184:187], v[228:231], v[38:41]
	v_mfma_f32_16x16x32_bf16 v[34:37], v[192:195], v[228:231], v[34:37]
	s_setprio 0
	s_barrier
	s_add_i32 s8, s49, s51
	v_lshl_add_u64 v[196:197], v[196:197], 0, s[14:15]
	s_mov_b32 m0, s8
	ds_read_b128 v[200:203], v174 offset:49152
	ds_read_b128 v[204:207], v174 offset:50176
	ds_read_b128 v[208:211], v174 offset:51200
	ds_read_b128 v[212:215], v174 offset:52224
	ds_read_b128 v[216:219], v174 offset:53248
	ds_read_b128 v[220:223], v174 offset:54272
	ds_read_b128 v[224:227], v174 offset:55296
	ds_read_b128 v[228:231], v174 offset:56320
	global_load_lds_dwordx4 v[196:197], off
	v_lshl_add_u64 v[196:197], v[232:233], 0, s[14:15]
	s_add_i32 m0, s8, 0x2000
	s_add_i32 s8, s84, s51
	global_load_lds_dwordx4 v[196:197], off
	v_lshl_add_u64 v[196:197], v[234:235], 0, s[14:15]
	s_mov_b32 m0, s8
	s_nop 0
	global_load_lds_dwordx4 v[196:197], off
	v_lshl_add_u64 v[196:197], v[236:237], 0, s[14:15]
	s_add_i32 m0, s8, 0x2000
	s_nop 0
	global_load_lds_dwordx4 v[196:197], off
	v_lshl_add_u64 v[196:197], v[238:239], 0, s[14:15]
	s_mov_b32 m0, s58
	s_nop 0
	global_load_lds_dwordx4 v[196:197], off
	v_lshl_add_u64 v[196:197], v[240:241], 0, s[14:15]
	s_mov_b32 m0, s59
	s_nop 0
	global_load_lds_dwordx4 v[196:197], off
	s_waitcnt vmcnt(8)
	s_waitcnt lgkmcnt(0)
	s_barrier
	s_setprio 1
	s_waitcnt lgkmcnt(0)
	v_mfma_f32_16x16x32_bf16 v[94:97], v[150:153], v[200:203], v[94:97]
	v_mfma_f32_16x16x32_bf16 v[90:93], v[158:161], v[200:203], v[90:93]
	v_mfma_f32_16x16x32_bf16 v[86:89], v[150:153], v[208:211], v[86:89]
	v_mfma_f32_16x16x32_bf16 v[82:85], v[158:161], v[208:211], v[82:85]
	v_mfma_f32_16x16x32_bf16 v[78:81], v[150:153], v[216:219], v[78:81]
	v_mfma_f32_16x16x32_bf16 v[74:77], v[158:161], v[216:219], v[74:77]
	v_mfma_f32_16x16x32_bf16 v[70:73], v[150:153], v[224:227], v[70:73]
	v_mfma_f32_16x16x32_bf16 v[66:69], v[158:161], v[224:227], v[66:69]
	v_mfma_f32_16x16x32_bf16 v[94:97], v[154:157], v[204:207], v[94:97]
	v_mfma_f32_16x16x32_bf16 v[90:93], v[162:165], v[204:207], v[90:93]
	v_mfma_f32_16x16x32_bf16 v[86:89], v[154:157], v[212:215], v[86:89]
	v_mfma_f32_16x16x32_bf16 v[82:85], v[162:165], v[212:215], v[82:85]
	v_mfma_f32_16x16x32_bf16 v[78:81], v[154:157], v[220:223], v[78:81]
	v_mfma_f32_16x16x32_bf16 v[74:77], v[162:165], v[220:223], v[74:77]
	v_mfma_f32_16x16x32_bf16 v[70:73], v[154:157], v[228:231], v[70:73]
	v_mfma_f32_16x16x32_bf16 v[66:69], v[162:165], v[228:231], v[66:69]
	s_setprio 0
	s_setprio 1
	v_mfma_f32_16x16x32_bf16 v[30:33], v[180:183], v[200:203], v[30:33]
	v_mfma_f32_16x16x32_bf16 v[26:29], v[188:191], v[200:203], v[26:29]
	v_mfma_f32_16x16x32_bf16 v[22:25], v[180:183], v[208:211], v[22:25]
	v_mfma_f32_16x16x32_bf16 v[18:21], v[188:191], v[208:211], v[18:21]
	v_mfma_f32_16x16x32_bf16 v[14:17], v[180:183], v[216:219], v[14:17]
	v_mfma_f32_16x16x32_bf16 v[10:13], v[188:191], v[216:219], v[10:13]
	v_mfma_f32_16x16x32_bf16 v[6:9], v[180:183], v[224:227], v[6:9]
	v_mfma_f32_16x16x32_bf16 v[2:5], v[188:191], v[224:227], v[2:5]
	v_mfma_f32_16x16x32_bf16 v[30:33], v[184:187], v[204:207], v[30:33]
	v_mfma_f32_16x16x32_bf16 v[26:29], v[192:195], v[204:207], v[26:29]
	v_mfma_f32_16x16x32_bf16 v[22:25], v[184:187], v[212:215], v[22:25]
	v_mfma_f32_16x16x32_bf16 v[18:21], v[192:195], v[212:215], v[18:21]
	v_mfma_f32_16x16x32_bf16 v[14:17], v[184:187], v[220:223], v[14:17]
	v_mfma_f32_16x16x32_bf16 v[10:13], v[192:195], v[220:223], v[10:13]
	v_mfma_f32_16x16x32_bf16 v[6:9], v[184:187], v[228:231], v[6:9]
	v_mfma_f32_16x16x32_bf16 v[2:5], v[192:195], v[228:231], v[2:5]
	s_setprio 0
	s_barrier
	s_add_u32 s6, s6, 0x100
	s_addc_u32 s7, s7, 0
	s_add_u32 s46, s46, 0x100
	s_addc_u32 s47, s47, 0
	s_cmp_ge_i32 s48, s61
	s_mov_b32 s8, s48
	s_cbranch_scc0 .LBB0_1556

.LBB0_1987:
	v_add_u32_e32 v2, s58, v199
	ds_read_b128 v[134:137], v2
	ds_read_b128 v[138:141], v2 offset:1024
	ds_read_b128 v[142:145], v2 offset:2048
	ds_read_b128 v[146:149], v2 offset:3072
	v_add_u32_e32 v2, s59, v199
	ds_read_b128 v[150:153], v2
	ds_read_b128 v[154:157], v2 offset:1024
	ds_read_b128 v[158:161], v2 offset:2048
	ds_read_b128 v[162:165], v2 offset:3072
	s_add_i32 s63, s40, 2
	s_add_u32 s64, s38, 0x80
	s_addc_u32 s41, s39, 0
	s_cmp_eq_u32 s57, s40
	s_cselect_b32 s40, s3, s64
	s_cselect_b32 s41, s1, s41
	s_cselect_b32 s65, s10, s62
	s_cselect_b32 s64, s27, s29
	s_cbranch_scc0 .Lpf_skip_4
	s_getpc_b64 s[98:99]
	s_mov_b32 m0, 0x22800
	v_lshlrev_b32_e32 v4, 7, v0
	global_load_lds_dword v4, s[98:99]
.Lpf_skip_4:
	v_lshl_add_u64 v[4:5], s[38:39], 0, v[212:213]
	s_add_i32 m0, s45, 0xc000
	ds_read_b128 v[166:169], v228
	ds_read_b128 v[170:173], v228 offset:1024
	ds_read_b128 v[174:177], v228 offset:2048
	ds_read_b128 v[178:181], v228 offset:3072
	ds_read_b128 v[182:185], v228 offset:4096
	ds_read_b128 v[186:189], v228 offset:5120
	ds_read_b128 v[190:193], v228 offset:6144
	ds_read_b128 v[194:197], v228 offset:7168
	global_load_lds_dwordx4 v[4:5], off
	v_lshl_add_u64 v[4:5], s[38:39], 0, v[214:215]
	s_add_i32 m0, s45, 0xe000
	s_nop 0
	global_load_lds_dwordx4 v[4:5], off
	s_waitcnt vmcnt(8)
	s_waitcnt lgkmcnt(0)
	s_barrier
	s_setprio 1
	s_waitcnt lgkmcnt(0)
	v_mfma_f32_16x16x32_bf16 v[130:133], v[134:137], v[166:169], v[130:133]
	v_mfma_f32_16x16x32_bf16 v[126:129], v[142:145], v[166:169], v[126:129]
	v_mfma_f32_16x16x32_bf16 v[122:125], v[134:137], v[174:177], v[122:125]
	v_mfma_f32_16x16x32_bf16 v[118:121], v[142:145], v[174:177], v[118:121]
	v_mfma_f32_16x16x32_bf16 v[114:117], v[134:137], v[182:185], v[114:117]
	v_mfma_f32_16x16x32_bf16 v[110:113], v[142:145], v[182:185], v[110:113]
	v_mfma_f32_16x16x32_bf16 v[106:109], v[134:137], v[190:193], v[106:109]
	v_mfma_f32_16x16x32_bf16 v[102:105], v[142:145], v[190:193], v[102:105]
	v_mfma_f32_16x16x32_bf16 v[130:133], v[138:141], v[170:173], v[130:133]
	v_mfma_f32_16x16x32_bf16 v[126:129], v[146:149], v[170:173], v[126:129]
	v_mfma_f32_16x16x32_bf16 v[122:125], v[138:141], v[178:181], v[122:125]
	v_mfma_f32_16x16x32_bf16 v[118:121], v[146:149], v[178:181], v[118:121]
	v_mfma_f32_16x16x32_bf16 v[114:117], v[138:141], v[186:189], v[114:117]
	v_mfma_f32_16x16x32_bf16 v[110:113], v[146:149], v[186:189], v[110:113]
	v_mfma_f32_16x16x32_bf16 v[106:109], v[138:141], v[194:197], v[106:109]
	v_mfma_f32_16x16x32_bf16 v[102:105], v[146:149], v[194:197], v[102:105]
	s_setprio 0
	s_setprio 1
	v_mfma_f32_16x16x32_bf16 v[98:101], v[150:153], v[166:169], v[98:101]
	v_mfma_f32_16x16x32_bf16 v[94:97], v[158:161], v[166:169], v[94:97]
	v_mfma_f32_16x16x32_bf16 v[90:93], v[150:153], v[174:177], v[90:93]
	v_mfma_f32_16x16x32_bf16 v[86:89], v[158:161], v[174:177], v[86:89]
	v_mfma_f32_16x16x32_bf16 v[82:85], v[150:153], v[182:185], v[82:85]
	v_mfma_f32_16x16x32_bf16 v[78:81], v[158:161], v[182:185], v[78:81]
	v_mfma_f32_16x16x32_bf16 v[74:77], v[150:153], v[190:193], v[74:77]
	v_mfma_f32_16x16x32_bf16 v[70:73], v[158:161], v[190:193], v[70:73]
	v_mfma_f32_16x16x32_bf16 v[98:101], v[154:157], v[170:173], v[98:101]
	v_mfma_f32_16x16x32_bf16 v[94:97], v[162:165], v[170:173], v[94:97]
	v_mfma_f32_16x16x32_bf16 v[90:93], v[154:157], v[178:181], v[90:93]
	v_mfma_f32_16x16x32_bf16 v[86:89], v[162:165], v[178:181], v[86:89]
	v_mfma_f32_16x16x32_bf16 v[82:85], v[154:157], v[186:189], v[82:85]
	v_mfma_f32_16x16x32_bf16 v[78:81], v[162:165], v[186:189], v[78:81]
	v_mfma_f32_16x16x32_bf16 v[74:77], v[154:157], v[194:197], v[74:77]
	v_mfma_f32_16x16x32_bf16 v[70:73], v[162:165], v[194:197], v[70:73]
	s_setprio 0
	s_barrier
	s_add_i32 s66, s58, s2
	v_lshl_add_u64 v[216:217], s[64:65], 0, v[202:203]
	s_mov_b32 m0, s66
	ds_read_b128 v[166:169], v228 offset:16384
	ds_read_b128 v[170:173], v228 offset:17408
	ds_read_b128 v[174:177], v228 offset:18432
	ds_read_b128 v[178:181], v228 offset:19456
	ds_read_b128 v[182:185], v228 offset:20480
	ds_read_b128 v[186:189], v228 offset:21504
	ds_read_b128 v[190:193], v228 offset:22528
	ds_read_b128 v[194:197], v228 offset:23552
	global_load_lds_dwordx4 v[216:217], off
	s_add_i32 m0, s66, 0x2000
	v_lshl_add_u64 v[218:219], s[64:65], 0, v[206:207]
	s_add_u32 s64, s64, s8
	s_addc_u32 s65, s65, s9
	s_add_i32 s66, s59, s2
	global_load_lds_dwordx4 v[218:219], off
	v_lshl_add_u64 v[220:221], s[64:65], 0, v[202:203]
	s_mov_b32 m0, s66
	v_lshl_add_u64 v[222:223], s[64:65], 0, v[206:207]
	global_load_lds_dwordx4 v[220:221], off
	s_add_i32 m0, s66, 0x2000
	v_lshl_add_u64 v[230:231], s[40:41], 0, v[200:201]
	global_load_lds_dwordx4 v[222:223], off
	s_mov_b32 m0, s45
	v_lshl_add_u64 v[232:233], s[40:41], 0, v[204:205]
	global_load_lds_dwordx4 v[230:231], off
	s_mov_b32 m0, s46
	s_nop 0
	global_load_lds_dwordx4 v[232:233], off
	s_waitcnt vmcnt(8)
	s_waitcnt lgkmcnt(0)
	s_barrier
	s_setprio 1
	s_waitcnt lgkmcnt(0)
	v_mfma_f32_16x16x32_bf16 v[66:69], v[134:137], v[166:169], v[66:69]
	v_mfma_f32_16x16x32_bf16 v[62:65], v[142:145], v[166:169], v[62:65]
	v_mfma_f32_16x16x32_bf16 v[58:61], v[134:137], v[174:177], v[58:61]
	v_mfma_f32_16x16x32_bf16 v[54:57], v[142:145], v[174:177], v[54:57]
	v_mfma_f32_16x16x32_bf16 v[50:53], v[134:137], v[182:185], v[50:53]
	v_mfma_f32_16x16x32_bf16 v[46:49], v[142:145], v[182:185], v[46:49]
	v_mfma_f32_16x16x32_bf16 v[42:45], v[134:137], v[190:193], v[42:45]
	v_mfma_f32_16x16x32_bf16 v[38:41], v[142:145], v[190:193], v[38:41]
	v_mfma_f32_16x16x32_bf16 v[66:69], v[138:141], v[170:173], v[66:69]
	v_mfma_f32_16x16x32_bf16 v[62:65], v[146:149], v[170:173], v[62:65]
	v_mfma_f32_16x16x32_bf16 v[58:61], v[138:141], v[178:181], v[58:61]
	v_mfma_f32_16x16x32_bf16 v[54:57], v[146:149], v[178:181], v[54:57]
	v_mfma_f32_16x16x32_bf16 v[50:53], v[138:141], v[186:189], v[50:53]
	v_mfma_f32_16x16x32_bf16 v[46:49], v[146:149], v[186:189], v[46:49]
	v_mfma_f32_16x16x32_bf16 v[42:45], v[138:141], v[194:197], v[42:45]
	v_mfma_f32_16x16x32_bf16 v[38:41], v[146:149], v[194:197], v[38:41]
	s_setprio 0
	s_setprio 1
	v_mfma_f32_16x16x32_bf16 v[34:37], v[150:153], v[166:169], v[34:37]
	v_mfma_f32_16x16x32_bf16 v[30:33], v[158:161], v[166:169], v[30:33]
	v_mfma_f32_16x16x32_bf16 v[26:29], v[150:153], v[174:177], v[26:29]
	v_mfma_f32_16x16x32_bf16 v[22:25], v[158:161], v[174:177], v[22:25]
	v_mfma_f32_16x16x32_bf16 v[18:21], v[150:153], v[182:185], v[18:21]
	v_mfma_f32_16x16x32_bf16 v[14:17], v[158:161], v[182:185], v[14:17]
	v_mfma_f32_16x16x32_bf16 v[10:13], v[150:153], v[190:193], v[10:13]
	v_mfma_f32_16x16x32_bf16 v[4:7], v[158:161], v[190:193], v[6:9]
	v_mfma_f32_16x16x32_bf16 v[34:37], v[154:157], v[170:173], v[34:37]
	v_mfma_f32_16x16x32_bf16 v[30:33], v[162:165], v[170:173], v[30:33]
	v_mfma_f32_16x16x32_bf16 v[26:29], v[154:157], v[178:181], v[26:29]
	v_mfma_f32_16x16x32_bf16 v[22:25], v[162:165], v[178:181], v[22:25]
	v_mfma_f32_16x16x32_bf16 v[18:21], v[154:157], v[186:189], v[18:21]
	v_mfma_f32_16x16x32_bf16 v[14:17], v[162:165], v[186:189], v[14:17]
	v_mfma_f32_16x16x32_bf16 v[10:13], v[154:157], v[194:197], v[10:13]
	v_mfma_f32_16x16x32_bf16 v[4:7], v[162:165], v[194:197], v[4:7]
	s_setprio 0
	s_barrier
	s_add_i32 s64, 0, 0x18000
	v_add_u32_e32 v2, s64, v199
	s_add_i32 s65, 0, 0x1c000
	ds_read_b128 v[134:137], v2
	ds_read_b128 v[138:141], v2 offset:1024
	ds_read_b128 v[142:145], v2 offset:2048
	ds_read_b128 v[146:149], v2 offset:3072
	v_add_u32_e32 v2, s65, v199
	ds_read_b128 v[150:153], v2
	ds_read_b128 v[154:157], v2 offset:1024
	ds_read_b128 v[158:161], v2 offset:2048
	ds_read_b128 v[162:165], v2 offset:3072
	s_add_u32 s40, s40, s8
	s_addc_u32 s41, s41, s9
	s_mov_b32 m0, s47
	v_lshl_add_u64 v[8:9], s[40:41], 0, v[200:201]
	ds_read_b128 v[166:169], v228 offset:32768
	ds_read_b128 v[170:173], v228 offset:33792
	ds_read_b128 v[174:177], v228 offset:34816
	ds_read_b128 v[178:181], v228 offset:35840
	ds_read_b128 v[182:185], v228 offset:36864
	ds_read_b128 v[186:189], v228 offset:37888
	ds_read_b128 v[190:193], v228 offset:38912
	ds_read_b128 v[194:197], v228 offset:39936
	global_load_lds_dwordx4 v[8:9], off
	v_lshl_add_u64 v[8:9], s[40:41], 0, v[204:205]
	s_mov_b32 m0, s48
	s_nop 0
	global_load_lds_dwordx4 v[8:9], off
	s_waitcnt vmcnt(8)
	s_waitcnt lgkmcnt(0)
	s_barrier
	s_setprio 1
	s_waitcnt lgkmcnt(0)
	v_mfma_f32_16x16x32_bf16 v[130:133], v[134:137], v[166:169], v[130:133]
	v_mfma_f32_16x16x32_bf16 v[126:129], v[142:145], v[166:169], v[126:129]
	v_mfma_f32_16x16x32_bf16 v[122:125], v[134:137], v[174:177], v[122:125]
	v_mfma_f32_16x16x32_bf16 v[118:121], v[142:145], v[174:177], v[118:121]
	v_mfma_f32_16x16x32_bf16 v[114:117], v[134:137], v[182:185], v[114:117]
	v_mfma_f32_16x16x32_bf16 v[110:113], v[142:145], v[182:185], v[110:113]
	v_mfma_f32_16x16x32_bf16 v[106:109], v[134:137], v[190:193], v[106:109]
	v_mfma_f32_16x16x32_bf16 v[102:105], v[142:145], v[190:193], v[102:105]
	v_mfma_f32_16x16x32_bf16 v[130:133], v[138:141], v[170:173], v[130:133]
	v_mfma_f32_16x16x32_bf16 v[126:129], v[146:149], v[170:173], v[126:129]
	v_mfma_f32_16x16x32_bf16 v[122:125], v[138:141], v[178:181], v[122:125]
	v_mfma_f32_16x16x32_bf16 v[118:121], v[146:149], v[178:181], v[118:121]
	v_mfma_f32_16x16x32_bf16 v[114:117], v[138:141], v[186:189], v[114:117]
	v_mfma_f32_16x16x32_bf16 v[110:113], v[146:149], v[186:189], v[110:113]
	v_mfma_f32_16x16x32_bf16 v[106:109], v[138:141], v[194:197], v[106:109]
	v_mfma_f32_16x16x32_bf16 v[102:105], v[146:149], v[194:197], v[102:105]
	s_setprio 0
	s_setprio 1
	v_mfma_f32_16x16x32_bf16 v[98:101], v[150:153], v[166:169], v[98:101]
	v_mfma_f32_16x16x32_bf16 v[94:97], v[158:161], v[166:169], v[94:97]
	v_mfma_f32_16x16x32_bf16 v[90:93], v[150:153], v[174:177], v[90:93]
	v_mfma_f32_16x16x32_bf16 v[86:89], v[158:161], v[174:177], v[86:89]
	v_mfma_f32_16x16x32_bf16 v[82:85], v[150:153], v[182:185], v[82:85]
	v_mfma_f32_16x16x32_bf16 v[78:81], v[158:161], v[182:185], v[78:81]
	v_mfma_f32_16x16x32_bf16 v[74:77], v[150:153], v[190:193], v[74:77]
	v_mfma_f32_16x16x32_bf16 v[70:73], v[158:161], v[190:193], v[70:73]
	v_mfma_f32_16x16x32_bf16 v[98:101], v[154:157], v[170:173], v[98:101]
	v_mfma_f32_16x16x32_bf16 v[94:97], v[162:165], v[170:173], v[94:97]
	v_mfma_f32_16x16x32_bf16 v[90:93], v[154:157], v[178:181], v[90:93]
	v_mfma_f32_16x16x32_bf16 v[86:89], v[162:165], v[178:181], v[86:89]
	v_mfma_f32_16x16x32_bf16 v[82:85], v[154:157], v[186:189], v[82:85]
	v_mfma_f32_16x16x32_bf16 v[78:81], v[162:165], v[186:189], v[78:81]
	v_mfma_f32_16x16x32_bf16 v[74:77], v[154:157], v[194:197], v[74:77]
	v_mfma_f32_16x16x32_bf16 v[70:73], v[162:165], v[194:197], v[70:73]
	s_setprio 0
	s_barrier
	s_add_i32 s40, s64, s2
	v_lshl_add_u64 v[8:9], v[216:217], 0, s[14:15]
	s_mov_b32 m0, s40
	ds_read_b128 v[166:169], v228 offset:49152
	ds_read_b128 v[170:173], v228 offset:50176
	ds_read_b128 v[174:177], v228 offset:51200
	ds_read_b128 v[178:181], v228 offset:52224
	ds_read_b128 v[182:185], v228 offset:53248
	ds_read_b128 v[186:189], v228 offset:54272
	ds_read_b128 v[190:193], v228 offset:55296
	ds_read_b128 v[194:197], v228 offset:56320
	global_load_lds_dwordx4 v[8:9], off
	v_lshl_add_u64 v[8:9], v[218:219], 0, s[14:15]
	s_add_i32 m0, s40, 0x2000
	s_add_i32 s40, s65, s2
	global_load_lds_dwordx4 v[8:9], off
	v_lshl_add_u64 v[8:9], v[220:221], 0, s[14:15]
	s_mov_b32 m0, s40
	s_nop 0
	global_load_lds_dwordx4 v[8:9], off
	v_lshl_add_u64 v[8:9], v[222:223], 0, s[14:15]
	s_add_i32 m0, s40, 0x2000
	s_nop 0
	global_load_lds_dwordx4 v[8:9], off
	v_lshl_add_u64 v[8:9], v[230:231], 0, s[14:15]
	s_mov_b32 m0, s54
	s_nop 0
	global_load_lds_dwordx4 v[8:9], off
	v_lshl_add_u64 v[8:9], v[232:233], 0, s[14:15]
	s_mov_b32 m0, s55
	s_nop 0
	global_load_lds_dwordx4 v[8:9], off
	s_waitcnt vmcnt(8)
	s_waitcnt lgkmcnt(0)
	s_barrier
	s_setprio 1
	s_waitcnt lgkmcnt(0)
	v_mfma_f32_16x16x32_bf16 v[66:69], v[134:137], v[166:169], v[66:69]
	v_mfma_f32_16x16x32_bf16 v[62:65], v[142:145], v[166:169], v[62:65]
	v_mfma_f32_16x16x32_bf16 v[58:61], v[134:137], v[174:177], v[58:61]
	v_mfma_f32_16x16x32_bf16 v[54:57], v[142:145], v[174:177], v[54:57]
	v_mfma_f32_16x16x32_bf16 v[50:53], v[134:137], v[182:185], v[50:53]
	v_mfma_f32_16x16x32_bf16 v[46:49], v[142:145], v[182:185], v[46:49]
	v_mfma_f32_16x16x32_bf16 v[42:45], v[134:137], v[190:193], v[42:45]
	v_mfma_f32_16x16x32_bf16 v[38:41], v[142:145], v[190:193], v[38:41]
	v_mfma_f32_16x16x32_bf16 v[66:69], v[138:141], v[170:173], v[66:69]
	v_mfma_f32_16x16x32_bf16 v[62:65], v[146:149], v[170:173], v[62:65]
	v_mfma_f32_16x16x32_bf16 v[58:61], v[138:141], v[178:181], v[58:61]
	v_mfma_f32_16x16x32_bf16 v[54:57], v[146:149], v[178:181], v[54:57]
	v_mfma_f32_16x16x32_bf16 v[50:53], v[138:141], v[186:189], v[50:53]
	v_mfma_f32_16x16x32_bf16 v[46:49], v[146:149], v[186:189], v[46:49]
	v_mfma_f32_16x16x32_bf16 v[42:45], v[138:141], v[194:197], v[42:45]
	v_mfma_f32_16x16x32_bf16 v[38:41], v[146:149], v[194:197], v[38:41]
	s_setprio 0
	s_setprio 1
	v_mfma_f32_16x16x32_bf16 v[34:37], v[150:153], v[166:169], v[34:37]
	v_mfma_f32_16x16x32_bf16 v[30:33], v[158:161], v[166:169], v[30:33]
	v_mfma_f32_16x16x32_bf16 v[26:29], v[150:153], v[174:177], v[26:29]
	v_mfma_f32_16x16x32_bf16 v[22:25], v[158:161], v[174:177], v[22:25]
	v_mfma_f32_16x16x32_bf16 v[18:21], v[150:153], v[182:185], v[18:21]
	v_mfma_f32_16x16x32_bf16 v[14:17], v[158:161], v[182:185], v[14:17]
	v_mfma_f32_16x16x32_bf16 v[8:11], v[150:153], v[190:193], v[10:13]
	v_mfma_f32_16x16x32_bf16 v[4:7], v[158:161], v[190:193], v[4:7]
	v_mfma_f32_16x16x32_bf16 v[34:37], v[154:157], v[170:173], v[34:37]
	v_mfma_f32_16x16x32_bf16 v[30:33], v[162:165], v[170:173], v[30:33]
	v_mfma_f32_16x16x32_bf16 v[26:29], v[154:157], v[178:181], v[26:29]
	v_mfma_f32_16x16x32_bf16 v[22:25], v[162:165], v[178:181], v[22:25]
	v_mfma_f32_16x16x32_bf16 v[18:21], v[154:157], v[186:189], v[18:21]
	v_mfma_f32_16x16x32_bf16 v[14:17], v[162:165], v[186:189], v[14:17]
	v_mfma_f32_16x16x32_bf16 v[10:13], v[154:157], v[194:197], v[8:11]
	v_mfma_f32_16x16x32_bf16 v[6:9], v[162:165], v[194:197], v[4:7]
	s_setprio 0
	s_barrier
	s_add_u32 s38, s38, 0x100
	s_addc_u32 s39, s39, 0
	s_add_u32 s29, s29, 0x100
	s_addc_u32 s62, s62, 0
	s_cmp_ge_i32 s63, s53
	s_mov_b32 s40, s63
	s_cbranch_scc0 .LBB0_1987

.LBB0_2160:
	s_waitcnt lgkmcnt(0)
	ds_read_b128 v[130:133], v220
	ds_read_b128 v[134:137], v220 offset:1024
	ds_read_b128 v[138:141], v220 offset:2048
	ds_read_b128 v[142:145], v220 offset:3072
	ds_read_b128 v[146:149], v221
	ds_read_b128 v[150:153], v221 offset:1024
	ds_read_b128 v[154:157], v221 offset:2048
	ds_read_b128 v[158:161], v221 offset:3072
	s_add_i32 s62, s42, 2
	s_add_u32 s63, s40, 0x80
	s_addc_u32 s43, s41, 0
	s_cmp_eq_u32 s54, s42
	s_cselect_b32 s42, s29, s63
	s_cselect_b32 s43, s13, s43
	s_cselect_b32 s65, s31, s61
	s_cselect_b32 s64, s59, s60
	s_cbranch_scc0 .Lpf_skip_5
	s_getpc_b64 s[98:99]
	s_mov_b32 m0, 0x22800
	v_lshlrev_b32_e32 v214, 7, v0
	global_load_lds_dword v214, s[98:99]
.Lpf_skip_5:
	v_lshl_add_u64 v[214:215], s[40:41], 0, v[210:211]
	s_add_i32 m0, s3, 0xc000
	ds_read_b128 v[162:165], v222
	ds_read_b128 v[166:169], v222 offset:1024
	ds_read_b128 v[170:173], v222 offset:2048
	ds_read_b128 v[174:177], v222 offset:3072
	ds_read_b128 v[178:181], v222 offset:4096
	ds_read_b128 v[182:185], v222 offset:5120
	ds_read_b128 v[186:189], v222 offset:6144
	ds_read_b128 v[190:193], v222 offset:7168
	global_load_lds_dwordx4 v[214:215], off
	v_lshl_add_u64 v[214:215], s[40:41], 0, v[212:213]
	s_add_i32 m0, s3, 0xe000
	s_nop 0
	global_load_lds_dwordx4 v[214:215], off
	s_waitcnt vmcnt(8)
	s_waitcnt lgkmcnt(0)
	s_barrier
	s_setprio 1
	s_waitcnt lgkmcnt(0)
	v_mfma_f32_16x16x32_bf16 v[118:121], v[130:133], v[162:165], v[118:121]
	v_mfma_f32_16x16x32_bf16 v[126:129], v[138:141], v[162:165], v[126:129]
	v_mfma_f32_16x16x32_bf16 v[110:113], v[130:133], v[170:173], v[110:113]
	v_mfma_f32_16x16x32_bf16 v[106:109], v[138:141], v[170:173], v[106:109]
	v_mfma_f32_16x16x32_bf16 v[94:97], v[130:133], v[178:181], v[94:97]
	v_mfma_f32_16x16x32_bf16 v[90:93], v[138:141], v[178:181], v[90:93]
	v_mfma_f32_16x16x32_bf16 v[78:81], v[130:133], v[186:189], v[78:81]
	v_mfma_f32_16x16x32_bf16 v[74:77], v[138:141], v[186:189], v[74:77]
	v_mfma_f32_16x16x32_bf16 v[118:121], v[134:137], v[166:169], v[118:121]
	v_mfma_f32_16x16x32_bf16 v[126:129], v[142:145], v[166:169], v[126:129]
	v_mfma_f32_16x16x32_bf16 v[110:113], v[134:137], v[174:177], v[110:113]
	v_mfma_f32_16x16x32_bf16 v[106:109], v[142:145], v[174:177], v[106:109]
	v_mfma_f32_16x16x32_bf16 v[94:97], v[134:137], v[182:185], v[94:97]
	v_mfma_f32_16x16x32_bf16 v[90:93], v[142:145], v[182:185], v[90:93]
	v_mfma_f32_16x16x32_bf16 v[78:81], v[134:137], v[190:193], v[78:81]
	v_mfma_f32_16x16x32_bf16 v[74:77], v[142:145], v[190:193], v[74:77]
	s_setprio 0
	s_setprio 1
	v_mfma_f32_16x16x32_bf16 v[122:125], v[146:149], v[162:165], v[122:125]
	v_mfma_f32_16x16x32_bf16 v[114:117], v[154:157], v[162:165], v[114:117]
	v_mfma_f32_16x16x32_bf16 v[102:105], v[146:149], v[170:173], v[102:105]
	v_mfma_f32_16x16x32_bf16 v[98:101], v[154:157], v[170:173], v[98:101]
	v_mfma_f32_16x16x32_bf16 v[86:89], v[146:149], v[178:181], v[86:89]
	v_mfma_f32_16x16x32_bf16 v[82:85], v[154:157], v[178:181], v[82:85]
	v_mfma_f32_16x16x32_bf16 v[70:73], v[146:149], v[186:189], v[70:73]
	v_mfma_f32_16x16x32_bf16 v[66:69], v[154:157], v[186:189], v[66:69]
	v_mfma_f32_16x16x32_bf16 v[122:125], v[150:153], v[166:169], v[122:125]
	v_mfma_f32_16x16x32_bf16 v[114:117], v[158:161], v[166:169], v[114:117]
	v_mfma_f32_16x16x32_bf16 v[102:105], v[150:153], v[174:177], v[102:105]
	v_mfma_f32_16x16x32_bf16 v[98:101], v[158:161], v[174:177], v[98:101]
	v_mfma_f32_16x16x32_bf16 v[86:89], v[150:153], v[182:185], v[86:89]
	v_mfma_f32_16x16x32_bf16 v[82:85], v[158:161], v[182:185], v[82:85]
	v_mfma_f32_16x16x32_bf16 v[70:73], v[150:153], v[190:193], v[70:73]
	v_mfma_f32_16x16x32_bf16 v[66:69], v[158:161], v[190:193], v[66:69]
	s_setprio 0
	s_barrier
	s_add_i32 s63, s55, s2
	v_lshl_add_u64 v[214:215], s[64:65], 0, v[196:197]
	s_mov_b32 m0, s63
	ds_read_b128 v[162:165], v222 offset:16384
	ds_read_b128 v[166:169], v222 offset:17408
	ds_read_b128 v[170:173], v222 offset:18432
	ds_read_b128 v[174:177], v222 offset:19456
	ds_read_b128 v[178:181], v222 offset:20480
	ds_read_b128 v[182:185], v222 offset:21504
	ds_read_b128 v[186:189], v222 offset:22528
	ds_read_b128 v[190:193], v222 offset:23552
	global_load_lds_dwordx4 v[214:215], off
	s_add_i32 m0, s63, 0x2000
	v_lshl_add_u64 v[216:217], s[64:65], 0, v[202:203]
	s_add_u32 s64, s64, s14
	s_addc_u32 s65, s65, s15
	s_add_i32 s63, s56, s2
	global_load_lds_dwordx4 v[216:217], off
	v_lshl_add_u64 v[224:225], s[64:65], 0, v[196:197]
	s_mov_b32 m0, s63
	v_lshl_add_u64 v[226:227], s[64:65], 0, v[202:203]
	global_load_lds_dwordx4 v[224:225], off
	s_add_i32 m0, s63, 0x2000
	v_lshl_add_u64 v[228:229], s[42:43], 0, v[194:195]
	global_load_lds_dwordx4 v[226:227], off
	s_mov_b32 m0, s3
	v_lshl_add_u64 v[230:231], s[42:43], 0, v[200:201]
	global_load_lds_dwordx4 v[228:229], off
	s_mov_b32 m0, s47
	s_nop 0
	global_load_lds_dwordx4 v[230:231], off
	s_waitcnt vmcnt(8)
	s_waitcnt lgkmcnt(0)
	s_barrier
	s_setprio 1
	s_waitcnt lgkmcnt(0)
	v_mfma_f32_16x16x32_bf16 v[62:65], v[130:133], v[162:165], v[62:65]
	v_mfma_f32_16x16x32_bf16 v[58:61], v[138:141], v[162:165], v[58:61]
	v_mfma_f32_16x16x32_bf16 v[46:49], v[130:133], v[170:173], v[46:49]
	v_mfma_f32_16x16x32_bf16 v[42:45], v[138:141], v[170:173], v[42:45]
	v_mfma_f32_16x16x32_bf16 v[30:33], v[130:133], v[178:181], v[30:33]
	v_mfma_f32_16x16x32_bf16 v[26:29], v[138:141], v[178:181], v[26:29]
	v_mfma_f32_16x16x32_bf16 v[14:17], v[130:133], v[186:189], v[14:17]
	v_mfma_f32_16x16x32_bf16 v[10:13], v[138:141], v[186:189], v[10:13]
	v_mfma_f32_16x16x32_bf16 v[62:65], v[134:137], v[166:169], v[62:65]
	v_mfma_f32_16x16x32_bf16 v[58:61], v[142:145], v[166:169], v[58:61]
	v_mfma_f32_16x16x32_bf16 v[46:49], v[134:137], v[174:177], v[46:49]
	v_mfma_f32_16x16x32_bf16 v[42:45], v[142:145], v[174:177], v[42:45]
	v_mfma_f32_16x16x32_bf16 v[30:33], v[134:137], v[182:185], v[30:33]
	v_mfma_f32_16x16x32_bf16 v[26:29], v[142:145], v[182:185], v[26:29]
	v_mfma_f32_16x16x32_bf16 v[14:17], v[134:137], v[190:193], v[14:17]
	v_mfma_f32_16x16x32_bf16 v[10:13], v[142:145], v[190:193], v[10:13]
	s_setprio 0
	s_setprio 1
	v_mfma_f32_16x16x32_bf16 v[54:57], v[146:149], v[162:165], v[54:57]
	v_mfma_f32_16x16x32_bf16 v[50:53], v[154:157], v[162:165], v[50:53]
	v_mfma_f32_16x16x32_bf16 v[38:41], v[146:149], v[170:173], v[38:41]
	v_mfma_f32_16x16x32_bf16 v[34:37], v[154:157], v[170:173], v[34:37]
	v_mfma_f32_16x16x32_bf16 v[22:25], v[146:149], v[178:181], v[22:25]
	v_mfma_f32_16x16x32_bf16 v[18:21], v[154:157], v[178:181], v[18:21]
	v_mfma_f32_16x16x32_bf16 v[6:9], v[146:149], v[186:189], v[6:9]
	v_mfma_f32_16x16x32_bf16 v[2:5], v[154:157], v[186:189], v[2:5]
	v_mfma_f32_16x16x32_bf16 v[54:57], v[150:153], v[166:169], v[54:57]
	v_mfma_f32_16x16x32_bf16 v[50:53], v[158:161], v[166:169], v[50:53]
	v_mfma_f32_16x16x32_bf16 v[38:41], v[150:153], v[174:177], v[38:41]
	v_mfma_f32_16x16x32_bf16 v[34:37], v[158:161], v[174:177], v[34:37]
	v_mfma_f32_16x16x32_bf16 v[22:25], v[150:153], v[182:185], v[22:25]
	v_mfma_f32_16x16x32_bf16 v[18:21], v[158:161], v[182:185], v[18:21]
	v_mfma_f32_16x16x32_bf16 v[6:9], v[150:153], v[190:193], v[6:9]
	v_mfma_f32_16x16x32_bf16 v[2:5], v[158:161], v[190:193], v[2:5]
	s_setprio 0
	s_barrier
	s_add_i32 s63, 0, 0x18000
	s_add_i32 s64, 0, 0x1c000
	v_add_u32_e32 v142, s63, v199
	v_add_u32_e32 v158, s64, v199
	ds_read_b128 v[130:133], v142
	ds_read_b128 v[134:137], v142 offset:1024
	ds_read_b128 v[138:141], v142 offset:2048
	ds_read_b128 v[142:145], v142 offset:3072
	ds_read_b128 v[146:149], v158
	ds_read_b128 v[150:153], v158 offset:1024
	ds_read_b128 v[154:157], v158 offset:2048
	ds_read_b128 v[158:161], v158 offset:3072
	s_add_u32 s42, s42, s14
	s_addc_u32 s43, s43, s15
	s_mov_b32 m0, s48
	v_lshl_add_u64 v[232:233], s[42:43], 0, v[194:195]
	ds_read_b128 v[162:165], v222 offset:32768
	ds_read_b128 v[166:169], v222 offset:33792
	ds_read_b128 v[170:173], v222 offset:34816
	ds_read_b128 v[174:177], v222 offset:35840
	ds_read_b128 v[178:181], v222 offset:36864
	ds_read_b128 v[182:185], v222 offset:37888
	ds_read_b128 v[186:189], v222 offset:38912
	ds_read_b128 v[190:193], v222 offset:39936
	global_load_lds_dwordx4 v[232:233], off
	v_lshl_add_u64 v[232:233], s[42:43], 0, v[200:201]
	s_mov_b32 m0, s49
	s_nop 0
	global_load_lds_dwordx4 v[232:233], off
	s_waitcnt vmcnt(8)
	s_waitcnt lgkmcnt(0)
	s_barrier
	s_setprio 1
	s_waitcnt lgkmcnt(0)
	v_mfma_f32_16x16x32_bf16 v[118:121], v[130:133], v[162:165], v[118:121]
	v_mfma_f32_16x16x32_bf16 v[126:129], v[138:141], v[162:165], v[126:129]
	v_mfma_f32_16x16x32_bf16 v[110:113], v[130:133], v[170:173], v[110:113]
	v_mfma_f32_16x16x32_bf16 v[106:109], v[138:141], v[170:173], v[106:109]
	v_mfma_f32_16x16x32_bf16 v[94:97], v[130:133], v[178:181], v[94:97]
	v_mfma_f32_16x16x32_bf16 v[90:93], v[138:141], v[178:181], v[90:93]
	v_mfma_f32_16x16x32_bf16 v[78:81], v[130:133], v[186:189], v[78:81]
	v_mfma_f32_16x16x32_bf16 v[74:77], v[138:141], v[186:189], v[74:77]
	v_mfma_f32_16x16x32_bf16 v[118:121], v[134:137], v[166:169], v[118:121]
	v_mfma_f32_16x16x32_bf16 v[126:129], v[142:145], v[166:169], v[126:129]
	v_mfma_f32_16x16x32_bf16 v[110:113], v[134:137], v[174:177], v[110:113]
	v_mfma_f32_16x16x32_bf16 v[106:109], v[142:145], v[174:177], v[106:109]
	v_mfma_f32_16x16x32_bf16 v[94:97], v[134:137], v[182:185], v[94:97]
	v_mfma_f32_16x16x32_bf16 v[90:93], v[142:145], v[182:185], v[90:93]
	v_mfma_f32_16x16x32_bf16 v[78:81], v[134:137], v[190:193], v[78:81]
	v_mfma_f32_16x16x32_bf16 v[74:77], v[142:145], v[190:193], v[74:77]
	s_setprio 0
	s_setprio 1
	v_mfma_f32_16x16x32_bf16 v[122:125], v[146:149], v[162:165], v[122:125]
	v_mfma_f32_16x16x32_bf16 v[114:117], v[154:157], v[162:165], v[114:117]
	v_mfma_f32_16x16x32_bf16 v[102:105], v[146:149], v[170:173], v[102:105]
	v_mfma_f32_16x16x32_bf16 v[98:101], v[154:157], v[170:173], v[98:101]
	v_mfma_f32_16x16x32_bf16 v[86:89], v[146:149], v[178:181], v[86:89]
	v_mfma_f32_16x16x32_bf16 v[82:85], v[154:157], v[178:181], v[82:85]
	v_mfma_f32_16x16x32_bf16 v[70:73], v[146:149], v[186:189], v[70:73]
	v_mfma_f32_16x16x32_bf16 v[66:69], v[154:157], v[186:189], v[66:69]
	v_mfma_f32_16x16x32_bf16 v[122:125], v[150:153], v[166:169], v[122:125]
	v_mfma_f32_16x16x32_bf16 v[114:117], v[158:161], v[166:169], v[114:117]
	v_mfma_f32_16x16x32_bf16 v[102:105], v[150:153], v[174:177], v[102:105]
	v_mfma_f32_16x16x32_bf16 v[98:101], v[158:161], v[174:177], v[98:101]
	v_mfma_f32_16x16x32_bf16 v[86:89], v[150:153], v[182:185], v[86:89]
	v_mfma_f32_16x16x32_bf16 v[82:85], v[158:161], v[182:185], v[82:85]
	v_mfma_f32_16x16x32_bf16 v[70:73], v[150:153], v[190:193], v[70:73]
	v_mfma_f32_16x16x32_bf16 v[66:69], v[158:161], v[190:193], v[66:69]
	s_setprio 0
	s_barrier
	s_add_i32 s42, s63, s2
	v_lshl_add_u64 v[214:215], v[214:215], 0, s[20:21]
	s_mov_b32 m0, s42
	ds_read_b128 v[162:165], v222 offset:49152
	ds_read_b128 v[166:169], v222 offset:50176
	ds_read_b128 v[170:173], v222 offset:51200
	ds_read_b128 v[174:177], v222 offset:52224
	ds_read_b128 v[178:181], v222 offset:53248
	ds_read_b128 v[182:185], v222 offset:54272
	ds_read_b128 v[186:189], v222 offset:55296
	ds_read_b128 v[190:193], v222 offset:56320
	global_load_lds_dwordx4 v[214:215], off
	v_lshl_add_u64 v[214:215], v[216:217], 0, s[20:21]
	s_add_i32 m0, s42, 0x2000
	s_add_i32 s42, s64, s2
	global_load_lds_dwordx4 v[214:215], off
	v_lshl_add_u64 v[214:215], v[224:225], 0, s[20:21]
	s_mov_b32 m0, s42
	s_nop 0
	global_load_lds_dwordx4 v[214:215], off
	v_lshl_add_u64 v[214:215], v[226:227], 0, s[20:21]
	s_add_i32 m0, s42, 0x2000
	s_nop 0
	global_load_lds_dwordx4 v[214:215], off
	v_lshl_add_u64 v[214:215], v[228:229], 0, s[20:21]
	s_mov_b32 m0, s50
	s_nop 0
	global_load_lds_dwordx4 v[214:215], off
	v_lshl_add_u64 v[214:215], v[230:231], 0, s[20:21]
	s_mov_b32 m0, s51
	s_nop 0
	global_load_lds_dwordx4 v[214:215], off
	s_waitcnt vmcnt(8)
	s_waitcnt lgkmcnt(0)
	s_barrier
	s_setprio 1
	s_waitcnt lgkmcnt(0)
	v_mfma_f32_16x16x32_bf16 v[62:65], v[130:133], v[162:165], v[62:65]
	v_mfma_f32_16x16x32_bf16 v[58:61], v[138:141], v[162:165], v[58:61]
	v_mfma_f32_16x16x32_bf16 v[46:49], v[130:133], v[170:173], v[46:49]
	v_mfma_f32_16x16x32_bf16 v[42:45], v[138:141], v[170:173], v[42:45]
	v_mfma_f32_16x16x32_bf16 v[30:33], v[130:133], v[178:181], v[30:33]
	v_mfma_f32_16x16x32_bf16 v[26:29], v[138:141], v[178:181], v[26:29]
	v_mfma_f32_16x16x32_bf16 v[14:17], v[130:133], v[186:189], v[14:17]
	v_mfma_f32_16x16x32_bf16 v[10:13], v[138:141], v[186:189], v[10:13]
	v_mfma_f32_16x16x32_bf16 v[62:65], v[134:137], v[166:169], v[62:65]
	v_mfma_f32_16x16x32_bf16 v[58:61], v[142:145], v[166:169], v[58:61]
	v_mfma_f32_16x16x32_bf16 v[46:49], v[134:137], v[174:177], v[46:49]
	v_mfma_f32_16x16x32_bf16 v[42:45], v[142:145], v[174:177], v[42:45]
	v_mfma_f32_16x16x32_bf16 v[30:33], v[134:137], v[182:185], v[30:33]
	v_mfma_f32_16x16x32_bf16 v[26:29], v[142:145], v[182:185], v[26:29]
	v_mfma_f32_16x16x32_bf16 v[14:17], v[134:137], v[190:193], v[14:17]
	v_mfma_f32_16x16x32_bf16 v[10:13], v[142:145], v[190:193], v[10:13]
	s_setprio 0
	s_setprio 1
	v_mfma_f32_16x16x32_bf16 v[54:57], v[146:149], v[162:165], v[54:57]
	v_mfma_f32_16x16x32_bf16 v[50:53], v[154:157], v[162:165], v[50:53]
	v_mfma_f32_16x16x32_bf16 v[38:41], v[146:149], v[170:173], v[38:41]
	v_mfma_f32_16x16x32_bf16 v[34:37], v[154:157], v[170:173], v[34:37]
	v_mfma_f32_16x16x32_bf16 v[22:25], v[146:149], v[178:181], v[22:25]
	v_mfma_f32_16x16x32_bf16 v[18:21], v[154:157], v[178:181], v[18:21]
	v_mfma_f32_16x16x32_bf16 v[6:9], v[146:149], v[186:189], v[6:9]
	v_mfma_f32_16x16x32_bf16 v[2:5], v[154:157], v[186:189], v[2:5]
	v_mfma_f32_16x16x32_bf16 v[54:57], v[150:153], v[166:169], v[54:57]
	v_mfma_f32_16x16x32_bf16 v[50:53], v[158:161], v[166:169], v[50:53]
	v_mfma_f32_16x16x32_bf16 v[38:41], v[150:153], v[174:177], v[38:41]
	v_mfma_f32_16x16x32_bf16 v[34:37], v[158:161], v[174:177], v[34:37]
	v_mfma_f32_16x16x32_bf16 v[22:25], v[150:153], v[182:185], v[22:25]
	v_mfma_f32_16x16x32_bf16 v[18:21], v[158:161], v[182:185], v[18:21]
	v_mfma_f32_16x16x32_bf16 v[6:9], v[150:153], v[190:193], v[6:9]
	v_mfma_f32_16x16x32_bf16 v[2:5], v[158:161], v[190:193], v[2:5]
	s_setprio 0
	s_barrier
	s_add_u32 s40, s40, 0x100
	s_addc_u32 s41, s41, 0
	s_add_u32 s60, s60, 0x100
	s_addc_u32 s61, s61, 0
	s_cmp_ge_i32 s62, s53
	s_mov_b32 s42, s62
	s_cbranch_scc0 .LBB0_2160

.LBB0_2194:
	v_add_u32_e32 v103, s53, v146
	ds_read_b128 v[148:151], v103
	ds_read_b128 v[152:155], v103 offset:1024
	ds_read_b128 v[156:159], v103 offset:2048
	ds_read_b128 v[160:163], v103 offset:3072
	v_add_u32_e32 v103, s54, v146
	ds_read_b128 v[164:167], v103
	ds_read_b128 v[168:171], v103 offset:1024
	ds_read_b128 v[172:175], v103 offset:2048
	ds_read_b128 v[176:179], v103 offset:3072
	s_add_i32 s63, s36, 2
	s_add_u32 s64, s34, 0x80
	s_addc_u32 s37, s35, 0
	s_cmp_eq_u32 s52, s36
	s_cselect_b32 s36, s23, s64
	s_cselect_b32 s37, s21, s37
	s_cselect_b32 s65, s59, s62
	s_cselect_b32 s64, s60, s61
	s_cbranch_scc0 .Lpf_skip_6
	s_getpc_b64 s[98:99]
	s_mov_b32 m0, 0x22800
	v_lshlrev_b32_e32 v104, 7, v0
	global_load_lds_dword v104, s[98:99]
.Lpf_skip_6:
	s_mov_b32 m0, s55
	v_lshl_add_u64 v[104:105], s[34:35], 0, v[142:143]
	ds_read_b128 v[180:183], v147
	ds_read_b128 v[184:187], v147 offset:1024
	ds_read_b128 v[188:191], v147 offset:2048
	ds_read_b128 v[192:195], v147 offset:3072
	ds_read_b128 v[200:203], v147 offset:4096
	ds_read_b128 v[204:207], v147 offset:5120
	ds_read_b128 v[208:211], v147 offset:6144
	ds_read_b128 v[212:215], v147 offset:7168
	global_load_lds_dwordx4 v[104:105], off
	v_lshl_add_u64 v[104:105], s[34:35], 0, v[144:145]
	s_mov_b32 m0, s56
	s_nop 0
	global_load_lds_dwordx4 v[104:105], off
	s_waitcnt vmcnt(8)
	s_waitcnt lgkmcnt(0)
	s_barrier
	s_setprio 1
	s_waitcnt lgkmcnt(0)
	v_mfma_f32_16x16x32_bf16 v[130:133], v[148:151], v[180:183], v[130:133]
	v_mfma_f32_16x16x32_bf16 v[126:129], v[156:159], v[180:183], v[126:129]
	v_mfma_f32_16x16x32_bf16 v[114:117], v[148:151], v[188:191], v[114:117]
	v_mfma_f32_16x16x32_bf16 v[110:113], v[156:159], v[188:191], v[110:113]
	v_mfma_f32_16x16x32_bf16 v[94:97], v[148:151], v[200:203], v[94:97]
	v_mfma_f32_16x16x32_bf16 v[90:93], v[156:159], v[200:203], v[90:93]
	v_mfma_f32_16x16x32_bf16 v[78:81], v[148:151], v[208:211], v[78:81]
	v_mfma_f32_16x16x32_bf16 v[74:77], v[156:159], v[208:211], v[74:77]
	v_mfma_f32_16x16x32_bf16 v[130:133], v[152:155], v[184:187], v[130:133]
	v_mfma_f32_16x16x32_bf16 v[126:129], v[160:163], v[184:187], v[126:129]
	v_mfma_f32_16x16x32_bf16 v[114:117], v[152:155], v[192:195], v[114:117]
	v_mfma_f32_16x16x32_bf16 v[110:113], v[160:163], v[192:195], v[110:113]
	v_mfma_f32_16x16x32_bf16 v[94:97], v[152:155], v[204:207], v[94:97]
	v_mfma_f32_16x16x32_bf16 v[90:93], v[160:163], v[204:207], v[90:93]
	v_mfma_f32_16x16x32_bf16 v[78:81], v[152:155], v[212:215], v[78:81]
	v_mfma_f32_16x16x32_bf16 v[74:77], v[160:163], v[212:215], v[74:77]
	s_setprio 0
	s_setprio 1
	v_mfma_f32_16x16x32_bf16 v[122:125], v[164:167], v[180:183], v[122:125]
	v_mfma_f32_16x16x32_bf16 v[118:121], v[172:175], v[180:183], v[118:121]
	v_mfma_f32_16x16x32_bf16 v[104:107], v[164:167], v[188:191], v[106:109]
	v_mfma_f32_16x16x32_bf16 v[98:101], v[172:175], v[188:191], v[98:101]
	v_mfma_f32_16x16x32_bf16 v[86:89], v[164:167], v[200:203], v[86:89]
	v_mfma_f32_16x16x32_bf16 v[82:85], v[172:175], v[200:203], v[82:85]
	v_mfma_f32_16x16x32_bf16 v[70:73], v[164:167], v[208:211], v[70:73]
	v_mfma_f32_16x16x32_bf16 v[66:69], v[172:175], v[208:211], v[66:69]
	v_mfma_f32_16x16x32_bf16 v[122:125], v[168:171], v[184:187], v[122:125]
	v_mfma_f32_16x16x32_bf16 v[118:121], v[176:179], v[184:187], v[118:121]
	v_mfma_f32_16x16x32_bf16 v[104:107], v[168:171], v[192:195], v[104:107]
	v_mfma_f32_16x16x32_bf16 v[98:101], v[176:179], v[192:195], v[98:101]
	v_mfma_f32_16x16x32_bf16 v[86:89], v[168:171], v[204:207], v[86:89]
	v_mfma_f32_16x16x32_bf16 v[82:85], v[176:179], v[204:207], v[82:85]
	v_mfma_f32_16x16x32_bf16 v[70:73], v[168:171], v[212:215], v[70:73]
	v_mfma_f32_16x16x32_bf16 v[66:69], v[176:179], v[212:215], v[66:69]
	s_setprio 0
	s_barrier
	s_add_i32 s66, s53, s39
	v_lshl_add_u64 v[196:197], s[64:65], 0, v[138:139]
	s_mov_b32 m0, s66
	ds_read_b128 v[180:183], v147 offset:16384
	ds_read_b128 v[184:187], v147 offset:17408
	ds_read_b128 v[188:191], v147 offset:18432
	ds_read_b128 v[192:195], v147 offset:19456
	ds_read_b128 v[200:203], v147 offset:20480
	ds_read_b128 v[204:207], v147 offset:21504
	ds_read_b128 v[208:211], v147 offset:22528
	ds_read_b128 v[212:215], v147 offset:23552
	global_load_lds_dwordx4 v[196:197], off
	s_add_i32 m0, s66, 0x2000
	v_lshl_add_u64 v[216:217], s[64:65], 0, v[134:135]
	s_add_u32 s64, s64, s0
	s_addc_u32 s65, s65, s1
	s_add_i32 s66, s54, s39
	global_load_lds_dwordx4 v[216:217], off
	v_lshl_add_u64 v[218:219], s[64:65], 0, v[138:139]
	s_mov_b32 m0, s66
	v_lshl_add_u64 v[220:221], s[64:65], 0, v[134:135]
	global_load_lds_dwordx4 v[218:219], off
	s_add_i32 m0, s66, 0x2000
	v_lshl_add_u64 v[222:223], s[36:37], 0, v[140:141]
	global_load_lds_dwordx4 v[220:221], off
	s_mov_b32 m0, s40
	v_lshl_add_u64 v[224:225], s[36:37], 0, v[136:137]
	global_load_lds_dwordx4 v[222:223], off
	s_mov_b32 m0, s41
	s_nop 0
	global_load_lds_dwordx4 v[224:225], off
	s_waitcnt vmcnt(8)
	s_waitcnt lgkmcnt(0)
	s_barrier
	s_setprio 1
	s_waitcnt lgkmcnt(0)
	v_mfma_f32_16x16x32_bf16 v[62:65], v[148:151], v[180:183], v[62:65]
	v_mfma_f32_16x16x32_bf16 v[58:61], v[156:159], v[180:183], v[58:61]
	v_mfma_f32_16x16x32_bf16 v[46:49], v[148:151], v[188:191], v[46:49]
	v_mfma_f32_16x16x32_bf16 v[42:45], v[156:159], v[188:191], v[42:45]
	v_mfma_f32_16x16x32_bf16 v[30:33], v[148:151], v[200:203], v[30:33]
	v_mfma_f32_16x16x32_bf16 v[26:29], v[156:159], v[200:203], v[26:29]
	v_mfma_f32_16x16x32_bf16 v[14:17], v[148:151], v[208:211], v[14:17]
	v_mfma_f32_16x16x32_bf16 v[10:13], v[156:159], v[208:211], v[10:13]
	v_mfma_f32_16x16x32_bf16 v[62:65], v[152:155], v[184:187], v[62:65]
	v_mfma_f32_16x16x32_bf16 v[58:61], v[160:163], v[184:187], v[58:61]
	v_mfma_f32_16x16x32_bf16 v[46:49], v[152:155], v[192:195], v[46:49]
	v_mfma_f32_16x16x32_bf16 v[42:45], v[160:163], v[192:195], v[42:45]
	v_mfma_f32_16x16x32_bf16 v[30:33], v[152:155], v[204:207], v[30:33]
	v_mfma_f32_16x16x32_bf16 v[26:29], v[160:163], v[204:207], v[26:29]
	v_mfma_f32_16x16x32_bf16 v[14:17], v[152:155], v[212:215], v[14:17]
	v_mfma_f32_16x16x32_bf16 v[10:13], v[160:163], v[212:215], v[10:13]
	s_setprio 0
	s_setprio 1
	v_mfma_f32_16x16x32_bf16 v[54:57], v[164:167], v[180:183], v[54:57]
	v_mfma_f32_16x16x32_bf16 v[50:53], v[172:175], v[180:183], v[50:53]
	v_mfma_f32_16x16x32_bf16 v[38:41], v[164:167], v[188:191], v[38:41]
	v_mfma_f32_16x16x32_bf16 v[34:37], v[172:175], v[188:191], v[34:37]
	v_mfma_f32_16x16x32_bf16 v[22:25], v[164:167], v[200:203], v[22:25]
	v_mfma_f32_16x16x32_bf16 v[18:21], v[172:175], v[200:203], v[18:21]
	v_mfma_f32_16x16x32_bf16 v[6:9], v[164:167], v[208:211], v[6:9]
	v_mfma_f32_16x16x32_bf16 v[2:5], v[172:175], v[208:211], v[2:5]
	v_mfma_f32_16x16x32_bf16 v[54:57], v[168:171], v[184:187], v[54:57]
	v_mfma_f32_16x16x32_bf16 v[50:53], v[176:179], v[184:187], v[50:53]
	v_mfma_f32_16x16x32_bf16 v[38:41], v[168:171], v[192:195], v[38:41]
	v_mfma_f32_16x16x32_bf16 v[34:37], v[176:179], v[192:195], v[34:37]
	v_mfma_f32_16x16x32_bf16 v[22:25], v[168:171], v[204:207], v[22:25]
	v_mfma_f32_16x16x32_bf16 v[18:21], v[176:179], v[204:207], v[18:21]
	v_mfma_f32_16x16x32_bf16 v[6:9], v[168:171], v[212:215], v[6:9]
	v_mfma_f32_16x16x32_bf16 v[2:5], v[176:179], v[212:215], v[2:5]
	s_setprio 0
	s_barrier
	s_add_i32 s64, 0, 0x18000
	v_add_u32_e32 v103, s64, v146
	s_add_i32 s65, 0, 0x1c000
	ds_read_b128 v[148:151], v103
	ds_read_b128 v[152:155], v103 offset:1024
	ds_read_b128 v[156:159], v103 offset:2048
	ds_read_b128 v[160:163], v103 offset:3072
	v_add_u32_e32 v103, s65, v146
	ds_read_b128 v[164:167], v103
	ds_read_b128 v[168:171], v103 offset:1024
	ds_read_b128 v[172:175], v103 offset:2048
	ds_read_b128 v[176:179], v103 offset:3072
	s_add_u32 s36, s36, s0
	s_addc_u32 s37, s37, s1
	s_mov_b32 m0, s43
	v_lshl_add_u64 v[108:109], s[36:37], 0, v[140:141]
	ds_read_b128 v[180:183], v147 offset:32768
	ds_read_b128 v[184:187], v147 offset:33792
	ds_read_b128 v[188:191], v147 offset:34816
	ds_read_b128 v[192:195], v147 offset:35840
	ds_read_b128 v[200:203], v147 offset:36864
	ds_read_b128 v[204:207], v147 offset:37888
	ds_read_b128 v[208:211], v147 offset:38912
	ds_read_b128 v[212:215], v147 offset:39936
	global_load_lds_dwordx4 v[108:109], off
	v_lshl_add_u64 v[108:109], s[36:37], 0, v[136:137]
	s_mov_b32 m0, s47
	s_nop 0
	global_load_lds_dwordx4 v[108:109], off
	s_waitcnt vmcnt(8)
	s_waitcnt lgkmcnt(0)
	s_barrier
	s_setprio 1
	s_waitcnt lgkmcnt(0)
	v_mfma_f32_16x16x32_bf16 v[130:133], v[148:151], v[180:183], v[130:133]
	v_mfma_f32_16x16x32_bf16 v[126:129], v[156:159], v[180:183], v[126:129]
	v_mfma_f32_16x16x32_bf16 v[114:117], v[148:151], v[188:191], v[114:117]
	v_mfma_f32_16x16x32_bf16 v[108:111], v[156:159], v[188:191], v[110:113]
	v_mfma_f32_16x16x32_bf16 v[94:97], v[148:151], v[200:203], v[94:97]
	v_mfma_f32_16x16x32_bf16 v[90:93], v[156:159], v[200:203], v[90:93]
	v_mfma_f32_16x16x32_bf16 v[78:81], v[148:151], v[208:211], v[78:81]
	v_mfma_f32_16x16x32_bf16 v[74:77], v[156:159], v[208:211], v[74:77]
	v_mfma_f32_16x16x32_bf16 v[130:133], v[152:155], v[184:187], v[130:133]
	v_mfma_f32_16x16x32_bf16 v[126:129], v[160:163], v[184:187], v[126:129]
	v_mfma_f32_16x16x32_bf16 v[114:117], v[152:155], v[192:195], v[114:117]
	v_mfma_f32_16x16x32_bf16 v[110:113], v[160:163], v[192:195], v[108:111]
	v_mfma_f32_16x16x32_bf16 v[94:97], v[152:155], v[204:207], v[94:97]
	v_mfma_f32_16x16x32_bf16 v[90:93], v[160:163], v[204:207], v[90:93]
	v_mfma_f32_16x16x32_bf16 v[78:81], v[152:155], v[212:215], v[78:81]
	v_mfma_f32_16x16x32_bf16 v[74:77], v[160:163], v[212:215], v[74:77]
	s_setprio 0
	s_setprio 1
	v_mfma_f32_16x16x32_bf16 v[122:125], v[164:167], v[180:183], v[122:125]
	v_mfma_f32_16x16x32_bf16 v[118:121], v[172:175], v[180:183], v[118:121]
	v_mfma_f32_16x16x32_bf16 v[104:107], v[164:167], v[188:191], v[104:107]
	v_mfma_f32_16x16x32_bf16 v[98:101], v[172:175], v[188:191], v[98:101]
	v_mfma_f32_16x16x32_bf16 v[86:89], v[164:167], v[200:203], v[86:89]
	v_mfma_f32_16x16x32_bf16 v[82:85], v[172:175], v[200:203], v[82:85]
	v_mfma_f32_16x16x32_bf16 v[70:73], v[164:167], v[208:211], v[70:73]
	v_mfma_f32_16x16x32_bf16 v[66:69], v[172:175], v[208:211], v[66:69]
	v_mfma_f32_16x16x32_bf16 v[122:125], v[168:171], v[184:187], v[122:125]
	v_mfma_f32_16x16x32_bf16 v[118:121], v[176:179], v[184:187], v[118:121]
	v_mfma_f32_16x16x32_bf16 v[106:109], v[168:171], v[192:195], v[104:107]
	v_mfma_f32_16x16x32_bf16 v[98:101], v[176:179], v[192:195], v[98:101]
	v_mfma_f32_16x16x32_bf16 v[86:89], v[168:171], v[204:207], v[86:89]
	v_mfma_f32_16x16x32_bf16 v[82:85], v[176:179], v[204:207], v[82:85]
	v_mfma_f32_16x16x32_bf16 v[70:73], v[168:171], v[212:215], v[70:73]
	v_mfma_f32_16x16x32_bf16 v[66:69], v[176:179], v[212:215], v[66:69]
	s_setprio 0
	s_barrier
	s_add_i32 s36, s64, s39
	v_lshl_add_u64 v[104:105], v[196:197], 0, s[16:17]
	s_mov_b32 m0, s36
	ds_read_b128 v[180:183], v147 offset:49152
	ds_read_b128 v[184:187], v147 offset:50176
	ds_read_b128 v[188:191], v147 offset:51200
	ds_read_b128 v[192:195], v147 offset:52224
	ds_read_b128 v[200:203], v147 offset:53248
	ds_read_b128 v[204:207], v147 offset:54272
	ds_read_b128 v[208:211], v147 offset:55296
	ds_read_b128 v[212:215], v147 offset:56320
	global_load_lds_dwordx4 v[104:105], off
	v_lshl_add_u64 v[104:105], v[216:217], 0, s[16:17]
	s_add_i32 m0, s36, 0x2000
	s_add_i32 s36, s65, s39
	global_load_lds_dwordx4 v[104:105], off
	v_lshl_add_u64 v[104:105], v[218:219], 0, s[16:17]
	s_mov_b32 m0, s36
	s_nop 0
	global_load_lds_dwordx4 v[104:105], off
	v_lshl_add_u64 v[104:105], v[220:221], 0, s[16:17]
	s_add_i32 m0, s36, 0x2000
	s_nop 0
	global_load_lds_dwordx4 v[104:105], off
	v_lshl_add_u64 v[104:105], v[222:223], 0, s[16:17]
	s_mov_b32 m0, s49
	s_nop 0
	global_load_lds_dwordx4 v[104:105], off
	v_lshl_add_u64 v[104:105], v[224:225], 0, s[16:17]
	s_mov_b32 m0, s50
	s_nop 0
	global_load_lds_dwordx4 v[104:105], off
	s_waitcnt vmcnt(8)
	s_waitcnt lgkmcnt(0)
	s_barrier
	s_setprio 1
	s_waitcnt lgkmcnt(0)
	v_mfma_f32_16x16x32_bf16 v[62:65], v[148:151], v[180:183], v[62:65]
	v_mfma_f32_16x16x32_bf16 v[58:61], v[156:159], v[180:183], v[58:61]
	v_mfma_f32_16x16x32_bf16 v[46:49], v[148:151], v[188:191], v[46:49]
	v_mfma_f32_16x16x32_bf16 v[42:45], v[156:159], v[188:191], v[42:45]
	v_mfma_f32_16x16x32_bf16 v[30:33], v[148:151], v[200:203], v[30:33]
	v_mfma_f32_16x16x32_bf16 v[26:29], v[156:159], v[200:203], v[26:29]
	v_mfma_f32_16x16x32_bf16 v[14:17], v[148:151], v[208:211], v[14:17]
	v_mfma_f32_16x16x32_bf16 v[10:13], v[156:159], v[208:211], v[10:13]
	v_mfma_f32_16x16x32_bf16 v[62:65], v[152:155], v[184:187], v[62:65]
	v_mfma_f32_16x16x32_bf16 v[58:61], v[160:163], v[184:187], v[58:61]
	v_mfma_f32_16x16x32_bf16 v[46:49], v[152:155], v[192:195], v[46:49]
	v_mfma_f32_16x16x32_bf16 v[42:45], v[160:163], v[192:195], v[42:45]
	v_mfma_f32_16x16x32_bf16 v[30:33], v[152:155], v[204:207], v[30:33]
	v_mfma_f32_16x16x32_bf16 v[26:29], v[160:163], v[204:207], v[26:29]
	v_mfma_f32_16x16x32_bf16 v[14:17], v[152:155], v[212:215], v[14:17]
	v_mfma_f32_16x16x32_bf16 v[10:13], v[160:163], v[212:215], v[10:13]
	s_setprio 0
	s_setprio 1
	v_mfma_f32_16x16x32_bf16 v[54:57], v[164:167], v[180:183], v[54:57]
	v_mfma_f32_16x16x32_bf16 v[50:53], v[172:175], v[180:183], v[50:53]
	v_mfma_f32_16x16x32_bf16 v[38:41], v[164:167], v[188:191], v[38:41]
	v_mfma_f32_16x16x32_bf16 v[34:37], v[172:175], v[188:191], v[34:37]
	v_mfma_f32_16x16x32_bf16 v[22:25], v[164:167], v[200:203], v[22:25]
	v_mfma_f32_16x16x32_bf16 v[18:21], v[172:175], v[200:203], v[18:21]
	v_mfma_f32_16x16x32_bf16 v[6:9], v[164:167], v[208:211], v[6:9]
	v_mfma_f32_16x16x32_bf16 v[2:5], v[172:175], v[208:211], v[2:5]
	v_mfma_f32_16x16x32_bf16 v[54:57], v[168:171], v[184:187], v[54:57]
	v_mfma_f32_16x16x32_bf16 v[50:53], v[176:179], v[184:187], v[50:53]
	v_mfma_f32_16x16x32_bf16 v[38:41], v[168:171], v[192:195], v[38:41]
	v_mfma_f32_16x16x32_bf16 v[34:37], v[176:179], v[192:195], v[34:37]
	v_mfma_f32_16x16x32_bf16 v[22:25], v[168:171], v[204:207], v[22:25]
	v_mfma_f32_16x16x32_bf16 v[18:21], v[176:179], v[204:207], v[18:21]
	v_mfma_f32_16x16x32_bf16 v[6:9], v[168:171], v[212:215], v[6:9]
	v_mfma_f32_16x16x32_bf16 v[2:5], v[176:179], v[212:215], v[2:5]
	s_setprio 0
	s_barrier
	s_add_u32 s34, s34, 0x100
	s_addc_u32 s35, s35, 0
	s_add_u32 s61, s61, 0x100
	s_addc_u32 s62, s62, 0
	s_cmp_ge_i32 s63, s51
	s_mov_b32 s36, s63
	s_cbranch_scc0 .LBB0_2194
